# NSA top-16 via branch-free bit search + GEMM LDS XOR swizzle (conflict-free ds_read_b128)
# speedup vs baseline: 1.0286x; 1.0286x over previous
.LBB0_192:
	s_or_b64 exec, exec, s[0:1]
	v_lshlrev_b32_e32 v97, 3, v104
	v_lshrrev_b32_e32 v214, 3, v104
	v_and_b32_e32 v124, 56, v97
	v_and_b32_e32 v108, 15, v104
	v_mov_b32_e32 v101, 0
	v_mul_u32_u24_e32 v109, 0x48, v214
	v_lshlrev_b32_e32 v100, 1, v124
	v_readlane_b32 s40, v250, 24
	v_lshl_add_u32 v215, v109, 1, v100
	v_lshl_add_u64 v[128:129], s[90:91], 0, v[100:101]
	v_lshl_add_u64 v[130:131], s[92:93], 0, v[100:101]
	v_lshlrev_b32_e32 v100, 1, v108
	v_readlane_b32 s44, v250, 28
	v_readlane_b32 s45, v250, 29
	v_readlane_b32 s8, v250, 0
	v_readlane_b32 s10, v250, 2
	v_lshl_add_u64 v[132:133], s[44:45], 0, v[100:101]
	v_lshlrev_b32_e32 v100, 2, v108
	v_readlane_b32 s11, v250, 3
	s_waitcnt lgkmcnt(0)
	v_bfe_u32 v0, v104, 4, 2
	v_lshlrev_b32_e32 v105, 3, v0
	v_lshl_add_u64 v[134:135], s[10:11], 0, v[100:101]
	s_add_u32 s10, s44, 0x5800000
	v_lshlrev_b32_e32 v110, 4, v0
	v_lshlrev_b32_e32 v112, 2, v0
	v_and_b32_e32 v102, 7, v104
	s_addc_u32 s11, s45, 0
	v_and_b32_e32 v0, 0xc0, v64
	v_mov_b32_e32 v1, v101
	v_and_b32_e32 v114, 0x80, v65
	v_lshl_add_u64 v[0:1], s[10:11], 0, v[0:1]
	v_lshlrev_b32_e32 v2, 1, v102
	v_mov_b32_e32 v3, v101
	s_barrier
	v_or_b32_e32 v116, 16, v108
	v_readlane_b32 s41, v250, 25
	v_readlane_b32 s42, v250, 26
	v_readlane_b32 s43, v250, 27
	v_readlane_b32 s46, v250, 30
	v_readlane_b32 s47, v250, 31
	v_readlane_b32 s9, v250, 1
	v_readlane_b32 s13, v250, 5
	v_readlane_b32 s14, v250, 6
	v_readlane_b32 s15, v250, 7
	v_lshl_add_u64 v[0:1], v[0:1], 0, v[2:3]
	v_lshlrev_b32_e32 v2, 1, v114
	s_getreg_b32 s4, hwreg(HW_REG_XCC_ID, 0, 4)
	v_lshrrev_b32_e32 v111, 4, v104
	v_bfe_u32 v217, v214, 1, 3
	v_xor_b32_e32 v217, v217, v102
	v_lshlrev_b32_e32 v217, 4, v217
	v_lshl_add_u32 v215, v214, 7, v217
	v_add_u32_e32 v216, 0xd800, v215
	v_cmp_lt_u32_e64 s[0:1], 23, v116
	v_cmp_gt_u32_e64 s[2:3], 28, v116
	v_or_b32_e32 v118, 32, v108
	v_or_b32_e32 v126, 48, v108
	v_lshl_add_u64 v[136:137], v[0:1], 0, v[2:3]
	s_and_b32 s37, s4, 7
	v_lshl_add_u64 v[138:139], s[8:9], 0, v[100:101]
	s_mov_b32 s13, 0
	v_mov_b32_e32 v103, 0x11ff0
	s_mov_b64 s[14:15], 0x10000
	s_mov_b32 s38, 0x10000
	s_mov_b64 s[16:17], 0x20000
	s_mov_b32 s39, 0x20000
	s_mov_b64 s[18:19], 0x30000
	s_mov_b32 s40, 0x30000
	s_mov_b32 s41, 0x1ffa0
	s_mov_b32 s42, 0x1ffc0
	s_mov_b32 s43, 0x1ffe0
	s_mov_b32 s44, 0x1ff80
	v_mov_b32_e32 v113, 0x358637bd
	s_mov_b32 s45, 0x800000
	s_movk_i32 s46, 0x60
	v_mbcnt_hi_u32_b32 v121, -1, v35
	s_mov_b32 s47, 0
	v_readlane_b32 s48, v250, 32
	v_readlane_b32 s49, v250, 33
	v_readlane_b32 s50, v250, 34
	v_readlane_b32 s51, v250, 35
	v_readlane_b32 s52, v250, 36
	v_readlane_b32 s53, v250, 37
	v_readlane_b32 s54, v250, 38
	v_readlane_b32 s55, v250, 39
	v_readlane_b32 s12, v250, 4
	s_branch .LBB0_194

.LBB0_203:
	s_cmp_lt_i32 s24, 0
	s_cbranch_scc1 .LBB0_219
	s_lshr_b32 s4, s24, 3
	s_mul_hi_u32 s4, s4, 0x97b425f
	s_mul_i32 s5, s4, 0xd8
	s_sub_i32 s8, s24, s5
	s_lshl_b32 s5, s37, 4
	s_lshl_b32 s4, s4, 3
	s_add_i32 s4, s4, s5
	s_and_b32 s5, s8, 7
	s_or_b32 s4, s4, s5
	s_lshl_b32 s48, s4, 7
	s_lshl_b32 s4, s8, 4
	v_or_b32_e32 v100, s48, v214
	s_and_b32 s6, s4, 0xf80
	v_lshlrev_b64 v[0:1], 11, v[100:101]
	v_lshl_add_u64 v[140:141], v[128:129], 0, v[0:1]
	v_or_b32_e32 v0, s6, v214
	v_lshlrev_b32_e32 v100, 11, v0
	v_add_co_u32_e32 v32, vcc, s38, v140
	v_lshl_add_u64 v[142:143], v[130:131], 0, v[100:101]
	s_nop 0
	v_addc_co_u32_e32 v33, vcc, 0, v141, vcc
	v_add_co_u32_e32 v34, vcc, s38, v142
	global_load_dwordx4 v[0:3], v[140:141], off
	global_load_dwordx4 v[4:7], v[142:143], off
	v_addc_co_u32_e32 v35, vcc, 0, v143, vcc
	v_add_co_u32_e32 v36, vcc, s39, v140
	global_load_dwordx4 v[8:11], v[32:33], off
	s_nop 0
	v_addc_co_u32_e32 v37, vcc, 0, v141, vcc
	v_add_co_u32_e32 v38, vcc, s39, v142
	global_load_dwordx4 v[12:15], v[34:35], off
	s_nop 0
	v_addc_co_u32_e32 v39, vcc, 0, v143, vcc
	v_add_co_u32_e32 v40, vcc, s40, v140
	global_load_dwordx4 v[16:19], v[36:37], off
	s_nop 0
	v_addc_co_u32_e32 v41, vcc, 0, v141, vcc
	v_add_co_u32_e32 v42, vcc, s40, v142
	global_load_dwordx4 v[20:23], v[38:39], off
	s_nop 0
	v_addc_co_u32_e32 v43, vcc, 0, v143, vcc
	global_load_dwordx4 v[24:27], v[40:41], off
	global_load_dwordx4 v[28:31], v[42:43], off
	global_load_dwordx4 v[64:67], v[140:141], off offset:128
	global_load_dwordx4 v[68:71], v[142:143], off offset:128
	global_load_dwordx4 v[72:75], v[32:33], off offset:128
	global_load_dwordx4 v[76:79], v[34:35], off offset:128
	global_load_dwordx4 v[80:83], v[36:37], off offset:128
	global_load_dwordx4 v[84:87], v[38:39], off offset:128
	global_load_dwordx4 v[88:91], v[40:41], off offset:128
	global_load_dwordx4 v[92:95], v[42:43], off offset:128
	v_readfirstlane_b32 s4, v104
	s_and_b32 s49, s4, 64
	s_lshr_b32 s4, s4, 1
	s_and_b32 s50, s4, 0x7fffffc0
	v_or_b32_e32 v48, s49, v108
	v_mov_b32_e32 v44, 0
	s_movk_i32 s9, 0x90
	v_or_b32_e32 v49, s50, v108
	v_mul_u32_u24_e32 v48, 0x48, v48
	s_mov_b32 s5, 0
	s_movk_i32 s7, 0x80
	v_mov_b32_e32 v45, v44
	v_mov_b32_e32 v46, v44
	v_mov_b32_e32 v47, v44
	v_mov_b32_e32 v52, v44
	v_mad_u64_u32 v[144:145], s[24:25], v49, s9, v[110:111]
	v_lshl_add_u32 v100, v48, 1, v110
	v_bfe_u32 v217, v108, 1, 3
	v_lshlrev_b32_e32 v217, 4, v217
	v_xor_b32_e32 v217, v217, v110
	v_or_b32_e32 v218, s50, v108
	v_lshl_add_u32 v144, v218, 7, v217
	v_xor_b32_e32 v218, 64, v144
	v_or_b32_e32 v219, s49, v108
	v_lshl_add_u32 v100, v219, 7, v217
	v_xor_b32_e32 v219, 64, v100
	v_lshl_add_u64 v[146:147], v[140:141], 0, s[14:15]
	v_lshl_add_u64 v[148:149], v[142:143], 0, s[14:15]
	v_lshl_add_u64 v[150:151], v[140:141], 0, s[16:17]
	v_lshl_add_u64 v[152:153], v[142:143], 0, s[16:17]
	v_lshl_add_u64 v[154:155], v[140:141], 0, s[18:19]
	v_lshl_add_u64 v[156:157], v[142:143], 0, s[18:19]
	v_mov_b32_e32 v53, v44
	v_mov_b32_e32 v54, v44
	v_mov_b32_e32 v55, v44
	v_mov_b32_e32 v60, v44
	v_mov_b32_e32 v61, v44
	v_mov_b32_e32 v62, v44
	v_mov_b32_e32 v63, v44
	v_mov_b32_e32 v56, v44
	v_mov_b32_e32 v57, v44
	v_mov_b32_e32 v58, v44
	v_mov_b32_e32 v59, v44
	v_mov_b32_e32 v40, v44
	v_mov_b32_e32 v41, v44
	v_mov_b32_e32 v42, v44
	v_mov_b32_e32 v43, v44
	v_mov_b32_e32 v36, v44
	v_mov_b32_e32 v37, v44
	v_mov_b32_e32 v38, v44
	v_mov_b32_e32 v39, v44
	v_mov_b32_e32 v32, v44
	v_mov_b32_e32 v33, v44
	s_waitcnt vmcnt(15)
	ds_write_b128 v215, v[0:3]
	s_waitcnt vmcnt(14)
	ds_write_b128 v215, v[4:7] offset:36864
	s_waitcnt vmcnt(13)
	ds_write_b128 v215, v[8:11] offset:4096
	s_waitcnt vmcnt(12)
	ds_write_b128 v215, v[12:15] offset:40960
	s_waitcnt vmcnt(11)
	ds_write_b128 v215, v[16:19] offset:8192
	s_waitcnt vmcnt(10)
	ds_write_b128 v215, v[20:23] offset:45056
	s_waitcnt vmcnt(9)
	ds_write_b128 v215, v[24:27] offset:12288
	s_waitcnt vmcnt(8)
	ds_write_b128 v215, v[28:31] offset:49152
	v_mov_b32_e32 v34, v44
	v_mov_b32_e32 v35, v44
	v_mov_b32_e32 v28, v44
	v_mov_b32_e32 v29, v44
	v_mov_b32_e32 v30, v44
	v_mov_b32_e32 v31, v44
	v_mov_b32_e32 v24, v44
	v_mov_b32_e32 v25, v44
	v_mov_b32_e32 v26, v44
	v_mov_b32_e32 v27, v44
	v_mov_b32_e32 v20, v44
	v_mov_b32_e32 v21, v44
	v_mov_b32_e32 v22, v44
	v_mov_b32_e32 v23, v44
	v_mov_b32_e32 v16, v44
	v_mov_b32_e32 v17, v44
	v_mov_b32_e32 v18, v44
	v_mov_b32_e32 v19, v44
	v_mov_b32_e32 v12, v44
	v_mov_b32_e32 v13, v44
	v_mov_b32_e32 v14, v44
	v_mov_b32_e32 v15, v44
	v_mov_b32_e32 v8, v44
	v_mov_b32_e32 v9, v44
	v_mov_b32_e32 v10, v44
	v_mov_b32_e32 v11, v44
	v_mov_b32_e32 v4, v44
	v_mov_b32_e32 v5, v44
	v_mov_b32_e32 v6, v44
	v_mov_b32_e32 v7, v44
	v_mov_b32_e32 v0, v44
	v_mov_b32_e32 v1, v44
	v_mov_b32_e32 v2, v44
	v_mov_b32_e32 v3, v44
	v_mov_b32_e32 v48, v44
	v_mov_b32_e32 v49, v44
	v_mov_b32_e32 v50, v44
	v_mov_b32_e32 v51, v44
	s_waitcnt lgkmcnt(0)
	s_barrier
.LBB0_205:
	ds_read_b128 v[158:161], v144
	ds_read_b128 v[162:165], v100 offset:36864
	ds_read_b128 v[166:169], v100 offset:38912
	ds_read_b128 v[170:173], v144 offset:2048
	ds_read_b128 v[174:177], v100 offset:40960
	ds_read_b128 v[178:181], v100 offset:43008
	s_add_i32 s9, s5, 2
	s_waitcnt lgkmcnt(4)
	v_mfma_f32_16x16x32_bf16 v[44:47], v[158:161], v[162:165], v[44:47]
	s_cmp_lt_u32 s5, 14
	s_cselect_b32 s12, s7, 0x3c0
	s_lshl_b64 s[24:25], s[12:13], 1
	s_waitcnt lgkmcnt(3)
	v_mfma_f32_16x16x32_bf16 v[52:55], v[158:161], v[166:169], v[52:55]
	v_lshl_add_u64 v[182:183], v[140:141], 0, s[24:25]
	v_lshl_add_u64 v[184:185], v[142:143], 0, s[24:25]
	v_lshl_add_u64 v[186:187], v[146:147], 0, s[24:25]
	s_waitcnt lgkmcnt(1)
	v_mfma_f32_16x16x32_bf16 v[60:63], v[158:161], v[174:177], v[60:63]
	v_lshl_add_u64 v[188:189], v[148:149], 0, s[24:25]
	v_lshl_add_u64 v[190:191], v[150:151], 0, s[24:25]
	v_lshl_add_u64 v[192:193], v[152:153], 0, s[24:25]
	s_waitcnt lgkmcnt(0)
	v_mfma_f32_16x16x32_bf16 v[56:59], v[158:161], v[178:181], v[56:59]
	v_lshl_add_u64 v[194:195], v[154:155], 0, s[24:25]
	v_lshl_add_u64 v[198:199], v[156:157], 0, s[24:25]
	s_min_u32 s4, s5, 12
	v_mfma_f32_16x16x32_bf16 v[40:43], v[170:173], v[162:165], v[40:43]
	s_lshl_b32 s12, s4, 7
	s_addk_i32 s7, 0x80
	s_add_i32 s4, s12, 0x180
	v_mfma_f32_16x16x32_bf16 v[36:39], v[170:173], v[166:169], v[36:39]
	s_cmp_gt_u32 s5, 13
	v_mfma_f32_16x16x32_bf16 v[32:35], v[170:173], v[174:177], v[32:35]
	v_mfma_f32_16x16x32_bf16 v[28:31], v[170:173], v[178:181], v[28:31]
	ds_read_b128 v[158:161], v144 offset:4096
	ds_read_b128 v[170:173], v144 offset:6144
	s_waitcnt lgkmcnt(1)
	v_mfma_f32_16x16x32_bf16 v[24:27], v[158:161], v[162:165], v[24:27]
	v_mfma_f32_16x16x32_bf16 v[20:23], v[158:161], v[166:169], v[20:23]
	v_mfma_f32_16x16x32_bf16 v[16:19], v[158:161], v[174:177], v[16:19]
	v_mfma_f32_16x16x32_bf16 v[12:15], v[158:161], v[178:181], v[12:15]
	global_load_dwordx4 v[158:161], v[182:183], off
	s_waitcnt lgkmcnt(0)
	v_mfma_f32_16x16x32_bf16 v[8:11], v[170:173], v[162:165], v[8:11]
	global_load_dwordx4 v[162:165], v[184:185], off
	s_nop 0
	global_load_dwordx4 v[182:185], v[186:187], off
	s_nop 0
	global_load_dwordx4 v[186:189], v[188:189], off
	v_mfma_f32_16x16x32_bf16 v[4:7], v[170:173], v[166:169], v[4:7]
	global_load_dwordx4 v[166:169], v[190:191], off
	s_nop 0
	global_load_dwordx4 v[190:193], v[192:193], off
	s_nop 0
	global_load_dwordx4 v[194:197], v[194:195], off
	v_mfma_f32_16x16x32_bf16 v[0:3], v[170:173], v[174:177], v[0:3]
	global_load_dwordx4 v[174:177], v[198:199], off
	v_mfma_f32_16x16x32_bf16 v[48:51], v[170:173], v[178:181], v[48:51]
	ds_read_b128 v[170:173], v218
	ds_read_b128 v[178:181], v219 offset:36864
	ds_read_b128 v[198:201], v218 offset:2048
	ds_read_b128 v[202:205], v219 offset:38912
	ds_read_b128 v[206:209], v219 offset:40960
	ds_read_b128 v[210:213], v219 offset:43008
	s_mov_b32 s5, s13
	s_waitcnt lgkmcnt(4)
	v_mfma_f32_16x16x32_bf16 v[44:47], v[170:173], v[178:181], v[44:47]
	s_waitcnt lgkmcnt(2)
	v_mfma_f32_16x16x32_bf16 v[52:55], v[170:173], v[202:205], v[52:55]
	s_waitcnt lgkmcnt(1)
	v_mfma_f32_16x16x32_bf16 v[60:63], v[170:173], v[206:209], v[60:63]
	s_waitcnt lgkmcnt(0)
	v_mfma_f32_16x16x32_bf16 v[56:59], v[170:173], v[210:213], v[56:59]
	v_mfma_f32_16x16x32_bf16 v[40:43], v[198:201], v[178:181], v[40:43]
	v_mfma_f32_16x16x32_bf16 v[36:39], v[198:201], v[202:205], v[36:39]
	v_mfma_f32_16x16x32_bf16 v[32:35], v[198:201], v[206:209], v[32:35]
	v_mfma_f32_16x16x32_bf16 v[28:31], v[198:201], v[210:213], v[28:31]
	ds_read_b128 v[170:173], v218 offset:4096
	ds_read_b128 v[198:201], v218 offset:6144
	s_waitcnt vmcnt(15)
	ds_write_b128 v215, v[64:67] offset:18432
	s_waitcnt vmcnt(14)
	ds_write_b128 v215, v[68:71] offset:55296
	s_waitcnt vmcnt(13)
	ds_write_b128 v215, v[72:75] offset:22528
	s_waitcnt vmcnt(12)
	ds_write_b128 v215, v[76:79] offset:59392
	s_waitcnt vmcnt(11)
	ds_write_b128 v215, v[80:83] offset:26624
	s_waitcnt vmcnt(10)
	ds_write_b128 v215, v[84:87] offset:63488
	s_waitcnt vmcnt(9)
	ds_write_b128 v215, v[88:91] offset:30720
	s_waitcnt vmcnt(8)
	ds_write_b128 v216, v[92:95] offset:12288
	s_waitcnt lgkmcnt(0)
	s_barrier
	ds_read_b128 v[64:67], v144 offset:18432
	v_mfma_f32_16x16x32_bf16 v[24:27], v[170:173], v[178:181], v[24:27]
	ds_read_b128 v[72:75], v100 offset:55296
	ds_read_b128 v[80:83], v100 offset:57344
	ds_read_b128 v[68:71], v144 offset:20480
	v_lshl_add_u64 v[84:85], v[146:147], 0, s[4:5]
	v_lshl_add_u64 v[86:87], v[148:149], 0, s[4:5]
	v_mfma_f32_16x16x32_bf16 v[20:23], v[170:173], v[202:205], v[20:23]
	v_lshl_add_u64 v[88:89], v[150:151], 0, s[4:5]
	v_lshl_add_u64 v[90:91], v[152:153], 0, s[4:5]
	v_mfma_f32_16x16x32_bf16 v[16:19], v[170:173], v[206:209], v[16:19]
	v_mfma_f32_16x16x32_bf16 v[12:15], v[170:173], v[210:213], v[12:15]
	ds_read_b128 v[92:95], v100 offset:59392
	ds_read_b128 v[170:173], v100 offset:61440
	v_mfma_f32_16x16x32_bf16 v[8:11], v[198:201], v[178:181], v[8:11]
	ds_read_b128 v[76:79], v144 offset:22528
	ds_read_b128 v[178:181], v144 offset:24576
	v_mfma_f32_16x16x32_bf16 v[4:7], v[198:201], v[202:205], v[4:7]
	v_mfma_f32_16x16x32_bf16 v[0:3], v[198:201], v[206:209], v[0:3]
	s_waitcnt lgkmcnt(6)
	v_mfma_f32_16x16x32_bf16 v[44:47], v[64:67], v[72:75], v[44:47]
	s_waitcnt lgkmcnt(5)
	v_mfma_f32_16x16x32_bf16 v[52:55], v[64:67], v[80:83], v[52:55]
	s_waitcnt lgkmcnt(3)
	v_mfma_f32_16x16x32_bf16 v[60:63], v[64:67], v[92:95], v[60:63]
	s_waitcnt lgkmcnt(2)
	v_mfma_f32_16x16x32_bf16 v[56:59], v[64:67], v[170:173], v[56:59]
	v_lshl_add_u64 v[64:65], v[140:141], 0, s[12:13]
	global_load_dwordx4 v[64:67], v[64:65], off offset:384
	v_mfma_f32_16x16x32_bf16 v[40:43], v[68:71], v[72:75], v[40:43]
	v_mfma_f32_16x16x32_bf16 v[36:39], v[68:71], v[80:83], v[36:39]
	v_mfma_f32_16x16x32_bf16 v[32:35], v[68:71], v[92:95], v[32:35]
	v_mfma_f32_16x16x32_bf16 v[28:31], v[68:71], v[170:173], v[28:31]
	v_lshl_add_u64 v[68:69], v[142:143], 0, s[12:13]
	global_load_dwordx4 v[68:71], v[68:69], off offset:384
	v_mfma_f32_16x16x32_bf16 v[48:51], v[198:201], v[210:213], v[48:51]
	v_lshl_add_u64 v[198:199], v[154:155], 0, s[4:5]
	v_lshl_add_u64 v[200:201], v[156:157], 0, s[4:5]
	s_waitcnt lgkmcnt(1)
	v_mfma_f32_16x16x32_bf16 v[24:27], v[76:79], v[72:75], v[24:27]
	v_mfma_f32_16x16x32_bf16 v[20:23], v[76:79], v[80:83], v[20:23]
	v_mfma_f32_16x16x32_bf16 v[16:19], v[76:79], v[92:95], v[16:19]
	v_mfma_f32_16x16x32_bf16 v[12:15], v[76:79], v[170:173], v[12:15]
	s_waitcnt lgkmcnt(0)
	v_mfma_f32_16x16x32_bf16 v[8:11], v[178:181], v[72:75], v[8:11]
	global_load_dwordx4 v[72:75], v[84:85], off
	global_load_dwordx4 v[76:79], v[86:87], off
	v_mfma_f32_16x16x32_bf16 v[4:7], v[178:181], v[80:83], v[4:7]
	global_load_dwordx4 v[80:83], v[88:89], off
	global_load_dwordx4 v[84:87], v[90:91], off
	s_nop 0
	global_load_dwordx4 v[88:91], v[198:199], off
	v_mfma_f32_16x16x32_bf16 v[0:3], v[178:181], v[92:95], v[0:3]
	global_load_dwordx4 v[92:95], v[200:201], off
	v_mfma_f32_16x16x32_bf16 v[48:51], v[178:181], v[170:173], v[48:51]
	ds_read_b128 v[170:173], v218 offset:18432
	ds_read_b128 v[178:181], v219 offset:55296
	ds_read_b128 v[198:201], v218 offset:20480
	ds_read_b128 v[202:205], v219 offset:57344
	ds_read_b128 v[206:209], v219 offset:59392
	ds_read_b128 v[210:213], v219 offset:61440
	s_mov_b32 s5, s9
	s_waitcnt lgkmcnt(4)
	v_mfma_f32_16x16x32_bf16 v[44:47], v[170:173], v[178:181], v[44:47]
	s_waitcnt lgkmcnt(2)
	v_mfma_f32_16x16x32_bf16 v[52:55], v[170:173], v[202:205], v[52:55]
	s_waitcnt lgkmcnt(1)
	v_mfma_f32_16x16x32_bf16 v[60:63], v[170:173], v[206:209], v[60:63]
	s_waitcnt lgkmcnt(0)
	v_mfma_f32_16x16x32_bf16 v[56:59], v[170:173], v[210:213], v[56:59]
	v_mfma_f32_16x16x32_bf16 v[40:43], v[198:201], v[178:181], v[40:43]
	v_mfma_f32_16x16x32_bf16 v[36:39], v[198:201], v[202:205], v[36:39]
	v_mfma_f32_16x16x32_bf16 v[32:35], v[198:201], v[206:209], v[32:35]
	v_mfma_f32_16x16x32_bf16 v[28:31], v[198:201], v[210:213], v[28:31]
	ds_read_b128 v[170:173], v218 offset:22528
	ds_read_b128 v[198:201], v218 offset:24576
	s_waitcnt vmcnt(15)
	ds_write_b128 v215, v[158:161]
	s_waitcnt vmcnt(14)
	ds_write_b128 v215, v[162:165] offset:36864
	s_waitcnt vmcnt(13)
	ds_write_b128 v215, v[182:185] offset:4096
	s_waitcnt vmcnt(12)
	ds_write_b128 v215, v[186:189] offset:40960
	s_waitcnt vmcnt(11)
	ds_write_b128 v215, v[166:169] offset:8192
	s_waitcnt lgkmcnt(6)
	v_mfma_f32_16x16x32_bf16 v[24:27], v[170:173], v[178:181], v[24:27]
	s_waitcnt vmcnt(10)
	ds_write_b128 v215, v[190:193] offset:45056
	s_waitcnt vmcnt(9)
	ds_write_b128 v215, v[194:197] offset:12288
	s_waitcnt vmcnt(8)
	ds_write_b128 v215, v[174:177] offset:49152
	s_waitcnt lgkmcnt(0)
	s_barrier
	v_mfma_f32_16x16x32_bf16 v[20:23], v[170:173], v[202:205], v[20:23]
	v_mfma_f32_16x16x32_bf16 v[16:19], v[170:173], v[206:209], v[16:19]
	v_mfma_f32_16x16x32_bf16 v[12:15], v[170:173], v[210:213], v[12:15]
	v_mfma_f32_16x16x32_bf16 v[8:11], v[198:201], v[178:181], v[8:11]
	v_mfma_f32_16x16x32_bf16 v[4:7], v[198:201], v[202:205], v[4:7]
	v_mfma_f32_16x16x32_bf16 v[0:3], v[198:201], v[206:209], v[0:3]
	v_mfma_f32_16x16x32_bf16 v[48:51], v[198:201], v[210:213], v[48:51]
	s_cbranch_scc0 .LBB0_205
	s_or_b32 s52, s49, s6
	s_cmp_gt_u32 s8, 31
	s_mov_b64 s[4:5], -1
	s_cbranch_scc0 .LBB0_220
	s_cmp_lt_u32 s8, 48
	s_cbranch_scc1 .LBB0_221
	s_cmp_lt_u32 s8, 56
	s_cbranch_scc1 .LBB0_225
	s_cmp_lt_u32 s8, 64
	s_cbranch_scc1 .LBB0_233
	s_cmpk_lt_u32 s8, 0x48
	s_cbranch_scc1 .LBB0_546
	s_cmpk_lt_u32 s8, 0x50
	s_cbranch_scc1 .LBB0_547
	s_cmpk_lt_u32 s8, 0x70
	s_cbranch_scc1 .LBB0_548
	s_cmpk_lt_u32 s8, 0x90
	s_cbranch_scc1 .LBB0_549
	s_cmpk_lt_u32 s8, 0x98
	s_cbranch_scc1 .LBB0_550
	s_cmpk_lt_u32 s8, 0xa0
	s_mov_b64 s[6:7], 0
	s_cbranch_scc1 .LBB0_551
	s_cmpk_lt_u32 s8, 0xb0
	s_mov_b64 s[30:31], 0
	s_cbranch_scc1 .LBB0_552
	s_cmpk_eq_i32 s52, 0xb00
	s_cbranch_scc1 .LBB0_553
	s_cmpk_lt_u32 s52, 0xd40
	s_cselect_b64 s[8:9], -1, 0
	s_cmpk_gt_u32 s52, 0xd3f
	s_cselect_b64 s[28:29], -1, 0
	s_mov_b64 s[26:27], 0
	s_branch .LBB0_554

.LBB0_854:
	s_mov_b32 s2, s58
	v_writelane_b32 v250, s2, 40
	s_lshr_b32 s33, s58, 1
	s_waitcnt vmcnt(2)
	v_lshlrev_b64 v[16:17], 11, v[152:153]
	v_writelane_b32 v250, s3, 41
	v_lshlrev_b32_e32 v18, 7, v145
	v_readlane_b32 s48, v250, 24
	v_readlane_b32 s49, v250, 25
	v_readlane_b32 s60, v250, 36
	v_readlane_b32 s61, v250, 37
	s_mov_b64 s[48:49], s[60:61]
	v_lshl_add_u64 v[16:17], s[48:49], 0, v[16:17]
	v_mov_b32_e32 v19, v117
	v_lshl_add_u64 v[16:17], v[16:17], 0, v[18:19]
	v_lshlrev_b32_e32 v152, 1, v130
	v_mov_b32_e32 v153, v117
	v_lshl_add_u64 v[154:155], v[16:17], 0, v[152:153]
	v_mul_f32_e32 v16, v80, v60
	v_mul_f32_e32 v17, v80, v61
	v_mul_f32_e32 v20, v80, v62
	v_mul_f32_e32 v21, v80, v63
	v_cvt_pk_bf16_f32 v16, v16, v17
	v_cvt_pk_bf16_f32 v17, v20, v21
	global_store_dwordx2 v[154:155], v[16:17], off
	v_mul_f32_e32 v16, v80, v56
	v_mul_f32_e32 v17, v80, v57
	v_mul_f32_e32 v20, v80, v58
	v_mul_f32_e32 v21, v80, v59
	v_cvt_pk_bf16_f32 v16, v16, v17
	v_cvt_pk_bf16_f32 v17, v20, v21
	global_store_dwordx2 v[154:155], v[16:17], off offset:32
	v_mul_f32_e32 v16, v80, v52
	v_mul_f32_e32 v17, v80, v53
	v_mul_f32_e32 v20, v80, v54
	v_mul_f32_e32 v21, v80, v55
	v_cvt_pk_bf16_f32 v16, v16, v17
	v_cvt_pk_bf16_f32 v17, v20, v21
	global_store_dwordx2 v[154:155], v[16:17], off offset:64
	v_mul_f32_e32 v16, v80, v48
	v_mul_f32_e32 v17, v80, v49
	v_mul_f32_e32 v20, v80, v50
	v_mul_f32_e32 v21, v80, v51
	v_cvt_pk_bf16_f32 v16, v16, v17
	v_cvt_pk_bf16_f32 v17, v20, v21
	global_store_dwordx2 v[154:155], v[16:17], off offset:96
	v_lshlrev_b64 v[16:17], 11, v[150:151]
	v_lshl_add_u64 v[16:17], s[48:49], 0, v[16:17]
	v_lshl_add_u64 v[16:17], v[16:17], 0, v[18:19]
	v_lshl_add_u64 v[150:151], v[16:17], 0, v[152:153]
	v_mul_f32_e32 v16, v76, v44
	v_mul_f32_e32 v17, v76, v45
	v_cvt_pk_bf16_f32 v16, v16, v17
	v_mul_f32_e32 v18, v76, v46
	v_mul_f32_e32 v19, v76, v47
	v_cvt_pk_bf16_f32 v17, v18, v19
	global_store_dwordx2 v[150:151], v[16:17], off
	v_mul_f32_e32 v16, v76, v40
	v_mul_f32_e32 v17, v76, v41
	v_cvt_pk_bf16_f32 v16, v16, v17
	v_mul_f32_e32 v18, v76, v42
	v_mul_f32_e32 v19, v76, v43
	v_cvt_pk_bf16_f32 v17, v18, v19
	global_store_dwordx2 v[150:151], v[16:17], off offset:32
	v_mul_f32_e32 v16, v76, v36
	v_mul_f32_e32 v17, v76, v37
	v_cvt_pk_bf16_f32 v16, v16, v17
	v_readlane_b32 s40, v249, 12
	v_mul_f32_e32 v18, v76, v38
	v_mul_f32_e32 v19, v76, v39
	v_cvt_pk_bf16_f32 v17, v18, v19
	global_store_dwordx2 v[150:151], v[16:17], off offset:64
	v_mul_f32_e32 v16, v76, v32
	s_lshl_b32 s2, s38, 4
	v_cmp_eq_u32_e32 vcc, s33, v106
	v_readlane_b32 s41, v249, 13
	s_add_i32 s47, s33, -1
	v_mul_f32_e32 v17, v76, v33
	v_cvt_pk_bf16_f32 v16, v16, v17
	s_add_i32 s2, s2, 16
	s_or_b64 s[40:41], s[40:41], vcc
	v_cmp_eq_u32_e32 vcc, s47, v106
	v_mul_f32_e32 v18, v76, v34
	v_mul_f32_e32 v19, v76, v35
	v_cvt_pk_bf16_f32 v17, v18, v19
	global_store_dwordx2 v[150:151], v[16:17], off offset:96
	v_cmp_gt_u32_e64 s[38:39], s2, v106
	v_cmp_gt_u32_e64 s[2:3], s2, v166
	s_or_b64 s[40:41], s[40:41], vcc
	v_lshl_add_u32 v16, v106, 2, s42
	v_mov_b64_e32 v[72:73], 0
	s_mov_b32 s44, 0
	s_mov_b32 s48, 0x9800
	v_readlane_b32 s50, v250, 26
	v_readlane_b32 s51, v250, 27
	v_readlane_b32 s52, v250, 28
	v_readlane_b32 s53, v250, 29
	v_readlane_b32 s54, v250, 30
	v_readlane_b32 s55, v250, 31
	v_readlane_b32 s56, v250, 32
	v_readlane_b32 s57, v250, 33
	v_readlane_b32 s58, v250, 34
	v_readlane_b32 s59, v250, 35
	v_readlane_b32 s62, v250, 38
	v_readlane_b32 s63, v250, 39
	v_mov_b32_e32 v20, 0
	v_mov_b32_e32 v19, 0
	s_and_saveexec_b64 s[42:43], s[38:39]
	ds_read_b32 v20, v16 offset:37632
	s_mov_b64 exec, s[42:43]
	s_and_saveexec_b64 s[42:43], s[2:3]
	ds_read_b32 v19, v16 offset:39692
	s_mov_b64 exec, s[42:43]
	s_add_i32 s84, s46, 3
	s_waitcnt lgkmcnt(0)
	v_add_f32_e32 v20, v20, v19
	v_cmp_ge_u32_e32 vcc, s84, v165
	v_cndmask_b32_e64 v20, v20, v180, s[40:41]
	s_nop 1
	v_cndmask_b32_e32 v20, v181, v20, vcc
	v_ashrrev_i32_e32 v19, 31, v20
	v_or_b32_e32 v19, 0x80000000, v19
	v_xor_b32_e32 v20, v19, v20
	v_mov_b32_e32 v19, 0
	v_mov_b32_e32 v18, 0
	s_and_saveexec_b64 s[42:43], s[38:39]
	ds_read_b32 v19, v16 offset:37376
	s_mov_b64 exec, s[42:43]
	s_and_saveexec_b64 s[42:43], s[2:3]
	ds_read_b32 v18, v16 offset:39432
	s_mov_b64 exec, s[42:43]
	s_add_i32 s84, s46, 2
	s_waitcnt lgkmcnt(0)
	v_add_f32_e32 v19, v19, v18
	v_cmp_ge_u32_e32 vcc, s84, v165
	v_cndmask_b32_e64 v19, v19, v180, s[40:41]
	s_nop 1
	v_cndmask_b32_e32 v19, v181, v19, vcc
	v_ashrrev_i32_e32 v18, 31, v19
	v_or_b32_e32 v18, 0x80000000, v18
	v_xor_b32_e32 v19, v18, v19
	v_mov_b32_e32 v18, 0
	v_mov_b32_e32 v17, 0
	s_and_saveexec_b64 s[42:43], s[38:39]
	ds_read_b32 v18, v16 offset:37120
	s_mov_b64 exec, s[42:43]
	s_and_saveexec_b64 s[42:43], s[2:3]
	ds_read_b32 v17, v16 offset:39172
	s_mov_b64 exec, s[42:43]
	s_add_i32 s84, s46, 1
	s_waitcnt lgkmcnt(0)
	v_add_f32_e32 v18, v18, v17
	v_cmp_ge_u32_e32 vcc, s84, v165
	v_cndmask_b32_e64 v18, v18, v180, s[40:41]
	s_nop 1
	v_cndmask_b32_e32 v18, v181, v18, vcc
	v_ashrrev_i32_e32 v17, 31, v18
	v_or_b32_e32 v17, 0x80000000, v17
	v_xor_b32_e32 v18, v17, v18
	v_mov_b32_e32 v17, 0
	v_mov_b32_e32 v73, 0
	s_and_saveexec_b64 s[42:43], s[38:39]
	ds_read_b32 v17, v16 offset:36864
	s_mov_b64 exec, s[42:43]
	s_and_saveexec_b64 s[42:43], s[2:3]
	ds_read_b32 v73, v16 offset:38912
	s_mov_b64 exec, s[42:43]
	s_add_i32 s84, s46, 0
	s_waitcnt lgkmcnt(0)
	v_add_f32_e32 v17, v17, v73
	v_cmp_ge_u32_e32 vcc, s84, v165
	v_cndmask_b32_e64 v17, v17, v180, s[40:41]
	s_nop 1
	v_cndmask_b32_e32 v17, v181, v17, vcc
	v_ashrrev_i32_e32 v73, 31, v17
	v_or_b32_e32 v73, 0x80000000, v73
	v_xor_b32_e32 v17, v73, v17
	v_mov_b32_e32 v73, 0
	s_add_i32 s46, s46, 4
	s_mov_b32 s64, 0
	s_mov_b32 s65, 0
	s_mov_b32 s66, 0
	s_mov_b32 s67, 0
	s_or_b32 s68, s64, 0x80000000
	s_or_b32 s69, s65, 0x80000000
	s_or_b32 s70, s66, 0x80000000
	s_or_b32 s71, s67, 0x80000000
	v_cmp_le_u32_e64 s[76:77], s68, v17
	v_cmp_le_u32_e64 s[78:79], s69, v18
	v_cmp_le_u32_e64 s[80:81], s70, v19
	v_cmp_le_u32_e64 s[82:83], s71, v20
	s_bcnt1_i32_b64 s72, s[76:77]
	s_bcnt1_i32_b64 s73, s[78:79]
	s_bcnt1_i32_b64 s74, s[80:81]
	s_bcnt1_i32_b64 s75, s[82:83]
	s_cmp_ge_u32 s72, 16
	s_cselect_b32 s64, s68, s64
	s_cmp_ge_u32 s73, 16
	s_cselect_b32 s65, s69, s65
	s_cmp_ge_u32 s74, 16
	s_cselect_b32 s66, s70, s66
	s_cmp_ge_u32 s75, 16
	s_cselect_b32 s67, s71, s67
	s_or_b32 s68, s64, 0x40000000
	s_or_b32 s69, s65, 0x40000000
	s_or_b32 s70, s66, 0x40000000
	s_or_b32 s71, s67, 0x40000000
	v_cmp_le_u32_e64 s[76:77], s68, v17
	v_cmp_le_u32_e64 s[78:79], s69, v18
	v_cmp_le_u32_e64 s[80:81], s70, v19
	v_cmp_le_u32_e64 s[82:83], s71, v20
	s_bcnt1_i32_b64 s72, s[76:77]
	s_bcnt1_i32_b64 s73, s[78:79]
	s_bcnt1_i32_b64 s74, s[80:81]
	s_bcnt1_i32_b64 s75, s[82:83]
	s_cmp_ge_u32 s72, 16
	s_cselect_b32 s64, s68, s64
	s_cmp_ge_u32 s73, 16
	s_cselect_b32 s65, s69, s65
	s_cmp_ge_u32 s74, 16
	s_cselect_b32 s66, s70, s66
	s_cmp_ge_u32 s75, 16
	s_cselect_b32 s67, s71, s67
	s_or_b32 s68, s64, 0x20000000
	s_or_b32 s69, s65, 0x20000000
	s_or_b32 s70, s66, 0x20000000
	s_or_b32 s71, s67, 0x20000000
	v_cmp_le_u32_e64 s[76:77], s68, v17
	v_cmp_le_u32_e64 s[78:79], s69, v18
	v_cmp_le_u32_e64 s[80:81], s70, v19
	v_cmp_le_u32_e64 s[82:83], s71, v20
	s_bcnt1_i32_b64 s72, s[76:77]
	s_bcnt1_i32_b64 s73, s[78:79]
	s_bcnt1_i32_b64 s74, s[80:81]
	s_bcnt1_i32_b64 s75, s[82:83]
	s_cmp_ge_u32 s72, 16
	s_cselect_b32 s64, s68, s64
	s_cmp_ge_u32 s73, 16
	s_cselect_b32 s65, s69, s65
	s_cmp_ge_u32 s74, 16
	s_cselect_b32 s66, s70, s66
	s_cmp_ge_u32 s75, 16
	s_cselect_b32 s67, s71, s67
	s_or_b32 s68, s64, 0x10000000
	s_or_b32 s69, s65, 0x10000000
	s_or_b32 s70, s66, 0x10000000
	s_or_b32 s71, s67, 0x10000000
	v_cmp_le_u32_e64 s[76:77], s68, v17
	v_cmp_le_u32_e64 s[78:79], s69, v18
	v_cmp_le_u32_e64 s[80:81], s70, v19
	v_cmp_le_u32_e64 s[82:83], s71, v20
	s_bcnt1_i32_b64 s72, s[76:77]
	s_bcnt1_i32_b64 s73, s[78:79]
	s_bcnt1_i32_b64 s74, s[80:81]
	s_bcnt1_i32_b64 s75, s[82:83]
	s_cmp_ge_u32 s72, 16
	s_cselect_b32 s64, s68, s64
	s_cmp_ge_u32 s73, 16
	s_cselect_b32 s65, s69, s65
	s_cmp_ge_u32 s74, 16
	s_cselect_b32 s66, s70, s66
	s_cmp_ge_u32 s75, 16
	s_cselect_b32 s67, s71, s67
	s_or_b32 s68, s64, 0x8000000
	s_or_b32 s69, s65, 0x8000000
	s_or_b32 s70, s66, 0x8000000
	s_or_b32 s71, s67, 0x8000000
	v_cmp_le_u32_e64 s[76:77], s68, v17
	v_cmp_le_u32_e64 s[78:79], s69, v18
	v_cmp_le_u32_e64 s[80:81], s70, v19
	v_cmp_le_u32_e64 s[82:83], s71, v20
	s_bcnt1_i32_b64 s72, s[76:77]
	s_bcnt1_i32_b64 s73, s[78:79]
	s_bcnt1_i32_b64 s74, s[80:81]
	s_bcnt1_i32_b64 s75, s[82:83]
	s_cmp_ge_u32 s72, 16
	s_cselect_b32 s64, s68, s64
	s_cmp_ge_u32 s73, 16
	s_cselect_b32 s65, s69, s65
	s_cmp_ge_u32 s74, 16
	s_cselect_b32 s66, s70, s66
	s_cmp_ge_u32 s75, 16
	s_cselect_b32 s67, s71, s67
	s_or_b32 s68, s64, 0x4000000
	s_or_b32 s69, s65, 0x4000000
	s_or_b32 s70, s66, 0x4000000
	s_or_b32 s71, s67, 0x4000000
	v_cmp_le_u32_e64 s[76:77], s68, v17
	v_cmp_le_u32_e64 s[78:79], s69, v18
	v_cmp_le_u32_e64 s[80:81], s70, v19
	v_cmp_le_u32_e64 s[82:83], s71, v20
	s_bcnt1_i32_b64 s72, s[76:77]
	s_bcnt1_i32_b64 s73, s[78:79]
	s_bcnt1_i32_b64 s74, s[80:81]
	s_bcnt1_i32_b64 s75, s[82:83]
	s_cmp_ge_u32 s72, 16
	s_cselect_b32 s64, s68, s64
	s_cmp_ge_u32 s73, 16
	s_cselect_b32 s65, s69, s65
	s_cmp_ge_u32 s74, 16
	s_cselect_b32 s66, s70, s66
	s_cmp_ge_u32 s75, 16
	s_cselect_b32 s67, s71, s67
	s_or_b32 s68, s64, 0x2000000
	s_or_b32 s69, s65, 0x2000000
	s_or_b32 s70, s66, 0x2000000
	s_or_b32 s71, s67, 0x2000000
	v_cmp_le_u32_e64 s[76:77], s68, v17
	v_cmp_le_u32_e64 s[78:79], s69, v18
	v_cmp_le_u32_e64 s[80:81], s70, v19
	v_cmp_le_u32_e64 s[82:83], s71, v20
	s_bcnt1_i32_b64 s72, s[76:77]
	s_bcnt1_i32_b64 s73, s[78:79]
	s_bcnt1_i32_b64 s74, s[80:81]
	s_bcnt1_i32_b64 s75, s[82:83]
	s_cmp_ge_u32 s72, 16
	s_cselect_b32 s64, s68, s64
	s_cmp_ge_u32 s73, 16
	s_cselect_b32 s65, s69, s65
	s_cmp_ge_u32 s74, 16
	s_cselect_b32 s66, s70, s66
	s_cmp_ge_u32 s75, 16
	s_cselect_b32 s67, s71, s67
	s_or_b32 s68, s64, 0x1000000
	s_or_b32 s69, s65, 0x1000000
	s_or_b32 s70, s66, 0x1000000
	s_or_b32 s71, s67, 0x1000000
	v_cmp_le_u32_e64 s[76:77], s68, v17
	v_cmp_le_u32_e64 s[78:79], s69, v18
	v_cmp_le_u32_e64 s[80:81], s70, v19
	v_cmp_le_u32_e64 s[82:83], s71, v20
	s_bcnt1_i32_b64 s72, s[76:77]
	s_bcnt1_i32_b64 s73, s[78:79]
	s_bcnt1_i32_b64 s74, s[80:81]
	s_bcnt1_i32_b64 s75, s[82:83]
	s_cmp_ge_u32 s72, 16
	s_cselect_b32 s64, s68, s64
	s_cmp_ge_u32 s73, 16
	s_cselect_b32 s65, s69, s65
	s_cmp_ge_u32 s74, 16
	s_cselect_b32 s66, s70, s66
	s_cmp_ge_u32 s75, 16
	s_cselect_b32 s67, s71, s67
	s_or_b32 s68, s64, 0x800000
	s_or_b32 s69, s65, 0x800000
	s_or_b32 s70, s66, 0x800000
	s_or_b32 s71, s67, 0x800000
	v_cmp_le_u32_e64 s[76:77], s68, v17
	v_cmp_le_u32_e64 s[78:79], s69, v18
	v_cmp_le_u32_e64 s[80:81], s70, v19
	v_cmp_le_u32_e64 s[82:83], s71, v20
	s_bcnt1_i32_b64 s72, s[76:77]
	s_bcnt1_i32_b64 s73, s[78:79]
	s_bcnt1_i32_b64 s74, s[80:81]
	s_bcnt1_i32_b64 s75, s[82:83]
	s_cmp_ge_u32 s72, 16
	s_cselect_b32 s64, s68, s64
	s_cmp_ge_u32 s73, 16
	s_cselect_b32 s65, s69, s65
	s_cmp_ge_u32 s74, 16
	s_cselect_b32 s66, s70, s66
	s_cmp_ge_u32 s75, 16
	s_cselect_b32 s67, s71, s67
	s_or_b32 s68, s64, 0x400000
	s_or_b32 s69, s65, 0x400000
	s_or_b32 s70, s66, 0x400000
	s_or_b32 s71, s67, 0x400000
	v_cmp_le_u32_e64 s[76:77], s68, v17
	v_cmp_le_u32_e64 s[78:79], s69, v18
	v_cmp_le_u32_e64 s[80:81], s70, v19
	v_cmp_le_u32_e64 s[82:83], s71, v20
	s_bcnt1_i32_b64 s72, s[76:77]
	s_bcnt1_i32_b64 s73, s[78:79]
	s_bcnt1_i32_b64 s74, s[80:81]
	s_bcnt1_i32_b64 s75, s[82:83]
	s_cmp_ge_u32 s72, 16
	s_cselect_b32 s64, s68, s64
	s_cmp_ge_u32 s73, 16
	s_cselect_b32 s65, s69, s65
	s_cmp_ge_u32 s74, 16
	s_cselect_b32 s66, s70, s66
	s_cmp_ge_u32 s75, 16
	s_cselect_b32 s67, s71, s67
	s_or_b32 s68, s64, 0x200000
	s_or_b32 s69, s65, 0x200000
	s_or_b32 s70, s66, 0x200000
	s_or_b32 s71, s67, 0x200000
	v_cmp_le_u32_e64 s[76:77], s68, v17
	v_cmp_le_u32_e64 s[78:79], s69, v18
	v_cmp_le_u32_e64 s[80:81], s70, v19
	v_cmp_le_u32_e64 s[82:83], s71, v20
	s_bcnt1_i32_b64 s72, s[76:77]
	s_bcnt1_i32_b64 s73, s[78:79]
	s_bcnt1_i32_b64 s74, s[80:81]
	s_bcnt1_i32_b64 s75, s[82:83]
	s_cmp_ge_u32 s72, 16
	s_cselect_b32 s64, s68, s64
	s_cmp_ge_u32 s73, 16
	s_cselect_b32 s65, s69, s65
	s_cmp_ge_u32 s74, 16
	s_cselect_b32 s66, s70, s66
	s_cmp_ge_u32 s75, 16
	s_cselect_b32 s67, s71, s67
	s_or_b32 s68, s64, 0x100000
	s_or_b32 s69, s65, 0x100000
	s_or_b32 s70, s66, 0x100000
	s_or_b32 s71, s67, 0x100000
	v_cmp_le_u32_e64 s[76:77], s68, v17
	v_cmp_le_u32_e64 s[78:79], s69, v18
	v_cmp_le_u32_e64 s[80:81], s70, v19
	v_cmp_le_u32_e64 s[82:83], s71, v20
	s_bcnt1_i32_b64 s72, s[76:77]
	s_bcnt1_i32_b64 s73, s[78:79]
	s_bcnt1_i32_b64 s74, s[80:81]
	s_bcnt1_i32_b64 s75, s[82:83]
	s_cmp_ge_u32 s72, 16
	s_cselect_b32 s64, s68, s64
	s_cmp_ge_u32 s73, 16
	s_cselect_b32 s65, s69, s65
	s_cmp_ge_u32 s74, 16
	s_cselect_b32 s66, s70, s66
	s_cmp_ge_u32 s75, 16
	s_cselect_b32 s67, s71, s67
	s_or_b32 s68, s64, 0x80000
	s_or_b32 s69, s65, 0x80000
	s_or_b32 s70, s66, 0x80000
	s_or_b32 s71, s67, 0x80000
	v_cmp_le_u32_e64 s[76:77], s68, v17
	v_cmp_le_u32_e64 s[78:79], s69, v18
	v_cmp_le_u32_e64 s[80:81], s70, v19
	v_cmp_le_u32_e64 s[82:83], s71, v20
	s_bcnt1_i32_b64 s72, s[76:77]
	s_bcnt1_i32_b64 s73, s[78:79]
	s_bcnt1_i32_b64 s74, s[80:81]
	s_bcnt1_i32_b64 s75, s[82:83]
	s_cmp_ge_u32 s72, 16
	s_cselect_b32 s64, s68, s64
	s_cmp_ge_u32 s73, 16
	s_cselect_b32 s65, s69, s65
	s_cmp_ge_u32 s74, 16
	s_cselect_b32 s66, s70, s66
	s_cmp_ge_u32 s75, 16
	s_cselect_b32 s67, s71, s67
	s_or_b32 s68, s64, 0x40000
	s_or_b32 s69, s65, 0x40000
	s_or_b32 s70, s66, 0x40000
	s_or_b32 s71, s67, 0x40000
	v_cmp_le_u32_e64 s[76:77], s68, v17
	v_cmp_le_u32_e64 s[78:79], s69, v18
	v_cmp_le_u32_e64 s[80:81], s70, v19
	v_cmp_le_u32_e64 s[82:83], s71, v20
	s_bcnt1_i32_b64 s72, s[76:77]
	s_bcnt1_i32_b64 s73, s[78:79]
	s_bcnt1_i32_b64 s74, s[80:81]
	s_bcnt1_i32_b64 s75, s[82:83]
	s_cmp_ge_u32 s72, 16
	s_cselect_b32 s64, s68, s64
	s_cmp_ge_u32 s73, 16
	s_cselect_b32 s65, s69, s65
	s_cmp_ge_u32 s74, 16
	s_cselect_b32 s66, s70, s66
	s_cmp_ge_u32 s75, 16
	s_cselect_b32 s67, s71, s67
	s_or_b32 s68, s64, 0x20000
	s_or_b32 s69, s65, 0x20000
	s_or_b32 s70, s66, 0x20000
	s_or_b32 s71, s67, 0x20000
	v_cmp_le_u32_e64 s[76:77], s68, v17
	v_cmp_le_u32_e64 s[78:79], s69, v18
	v_cmp_le_u32_e64 s[80:81], s70, v19
	v_cmp_le_u32_e64 s[82:83], s71, v20
	s_bcnt1_i32_b64 s72, s[76:77]
	s_bcnt1_i32_b64 s73, s[78:79]
	s_bcnt1_i32_b64 s74, s[80:81]
	s_bcnt1_i32_b64 s75, s[82:83]
	s_cmp_ge_u32 s72, 16
	s_cselect_b32 s64, s68, s64
	s_cmp_ge_u32 s73, 16
	s_cselect_b32 s65, s69, s65
	s_cmp_ge_u32 s74, 16
	s_cselect_b32 s66, s70, s66
	s_cmp_ge_u32 s75, 16
	s_cselect_b32 s67, s71, s67
	s_or_b32 s68, s64, 0x10000
	s_or_b32 s69, s65, 0x10000
	s_or_b32 s70, s66, 0x10000
	s_or_b32 s71, s67, 0x10000
	v_cmp_le_u32_e64 s[76:77], s68, v17
	v_cmp_le_u32_e64 s[78:79], s69, v18
	v_cmp_le_u32_e64 s[80:81], s70, v19
	v_cmp_le_u32_e64 s[82:83], s71, v20
	s_bcnt1_i32_b64 s72, s[76:77]
	s_bcnt1_i32_b64 s73, s[78:79]
	s_bcnt1_i32_b64 s74, s[80:81]
	s_bcnt1_i32_b64 s75, s[82:83]
	s_cmp_ge_u32 s72, 16
	s_cselect_b32 s64, s68, s64
	s_cmp_ge_u32 s73, 16
	s_cselect_b32 s65, s69, s65
	s_cmp_ge_u32 s74, 16
	s_cselect_b32 s66, s70, s66
	s_cmp_ge_u32 s75, 16
	s_cselect_b32 s67, s71, s67
	s_or_b32 s68, s64, 0x8000
	s_or_b32 s69, s65, 0x8000
	s_or_b32 s70, s66, 0x8000
	s_or_b32 s71, s67, 0x8000
	v_cmp_le_u32_e64 s[76:77], s68, v17
	v_cmp_le_u32_e64 s[78:79], s69, v18
	v_cmp_le_u32_e64 s[80:81], s70, v19
	v_cmp_le_u32_e64 s[82:83], s71, v20
	s_bcnt1_i32_b64 s72, s[76:77]
	s_bcnt1_i32_b64 s73, s[78:79]
	s_bcnt1_i32_b64 s74, s[80:81]
	s_bcnt1_i32_b64 s75, s[82:83]
	s_cmp_ge_u32 s72, 16
	s_cselect_b32 s64, s68, s64
	s_cmp_ge_u32 s73, 16
	s_cselect_b32 s65, s69, s65
	s_cmp_ge_u32 s74, 16
	s_cselect_b32 s66, s70, s66
	s_cmp_ge_u32 s75, 16
	s_cselect_b32 s67, s71, s67
	s_or_b32 s68, s64, 0x4000
	s_or_b32 s69, s65, 0x4000
	s_or_b32 s70, s66, 0x4000
	s_or_b32 s71, s67, 0x4000
	v_cmp_le_u32_e64 s[76:77], s68, v17
	v_cmp_le_u32_e64 s[78:79], s69, v18
	v_cmp_le_u32_e64 s[80:81], s70, v19
	v_cmp_le_u32_e64 s[82:83], s71, v20
	s_bcnt1_i32_b64 s72, s[76:77]
	s_bcnt1_i32_b64 s73, s[78:79]
	s_bcnt1_i32_b64 s74, s[80:81]
	s_bcnt1_i32_b64 s75, s[82:83]
	s_cmp_ge_u32 s72, 16
	s_cselect_b32 s64, s68, s64
	s_cmp_ge_u32 s73, 16
	s_cselect_b32 s65, s69, s65
	s_cmp_ge_u32 s74, 16
	s_cselect_b32 s66, s70, s66
	s_cmp_ge_u32 s75, 16
	s_cselect_b32 s67, s71, s67
	s_or_b32 s68, s64, 0x2000
	s_or_b32 s69, s65, 0x2000
	s_or_b32 s70, s66, 0x2000
	s_or_b32 s71, s67, 0x2000
	v_cmp_le_u32_e64 s[76:77], s68, v17
	v_cmp_le_u32_e64 s[78:79], s69, v18
	v_cmp_le_u32_e64 s[80:81], s70, v19
	v_cmp_le_u32_e64 s[82:83], s71, v20
	s_bcnt1_i32_b64 s72, s[76:77]
	s_bcnt1_i32_b64 s73, s[78:79]
	s_bcnt1_i32_b64 s74, s[80:81]
	s_bcnt1_i32_b64 s75, s[82:83]
	s_cmp_ge_u32 s72, 16
	s_cselect_b32 s64, s68, s64
	s_cmp_ge_u32 s73, 16
	s_cselect_b32 s65, s69, s65
	s_cmp_ge_u32 s74, 16
	s_cselect_b32 s66, s70, s66
	s_cmp_ge_u32 s75, 16
	s_cselect_b32 s67, s71, s67
	s_or_b32 s68, s64, 0x1000
	s_or_b32 s69, s65, 0x1000
	s_or_b32 s70, s66, 0x1000
	s_or_b32 s71, s67, 0x1000
	v_cmp_le_u32_e64 s[76:77], s68, v17
	v_cmp_le_u32_e64 s[78:79], s69, v18
	v_cmp_le_u32_e64 s[80:81], s70, v19
	v_cmp_le_u32_e64 s[82:83], s71, v20
	s_bcnt1_i32_b64 s72, s[76:77]
	s_bcnt1_i32_b64 s73, s[78:79]
	s_bcnt1_i32_b64 s74, s[80:81]
	s_bcnt1_i32_b64 s75, s[82:83]
	s_cmp_ge_u32 s72, 16
	s_cselect_b32 s64, s68, s64
	s_cmp_ge_u32 s73, 16
	s_cselect_b32 s65, s69, s65
	s_cmp_ge_u32 s74, 16
	s_cselect_b32 s66, s70, s66
	s_cmp_ge_u32 s75, 16
	s_cselect_b32 s67, s71, s67
	s_or_b32 s68, s64, 0x800
	s_or_b32 s69, s65, 0x800
	s_or_b32 s70, s66, 0x800
	s_or_b32 s71, s67, 0x800
	v_cmp_le_u32_e64 s[76:77], s68, v17
	v_cmp_le_u32_e64 s[78:79], s69, v18
	v_cmp_le_u32_e64 s[80:81], s70, v19
	v_cmp_le_u32_e64 s[82:83], s71, v20
	s_bcnt1_i32_b64 s72, s[76:77]
	s_bcnt1_i32_b64 s73, s[78:79]
	s_bcnt1_i32_b64 s74, s[80:81]
	s_bcnt1_i32_b64 s75, s[82:83]
	s_cmp_ge_u32 s72, 16
	s_cselect_b32 s64, s68, s64
	s_cmp_ge_u32 s73, 16
	s_cselect_b32 s65, s69, s65
	s_cmp_ge_u32 s74, 16
	s_cselect_b32 s66, s70, s66
	s_cmp_ge_u32 s75, 16
	s_cselect_b32 s67, s71, s67
	s_or_b32 s68, s64, 0x400
	s_or_b32 s69, s65, 0x400
	s_or_b32 s70, s66, 0x400
	s_or_b32 s71, s67, 0x400
	v_cmp_le_u32_e64 s[76:77], s68, v17
	v_cmp_le_u32_e64 s[78:79], s69, v18
	v_cmp_le_u32_e64 s[80:81], s70, v19
	v_cmp_le_u32_e64 s[82:83], s71, v20
	s_bcnt1_i32_b64 s72, s[76:77]
	s_bcnt1_i32_b64 s73, s[78:79]
	s_bcnt1_i32_b64 s74, s[80:81]
	s_bcnt1_i32_b64 s75, s[82:83]
	s_cmp_ge_u32 s72, 16
	s_cselect_b32 s64, s68, s64
	s_cmp_ge_u32 s73, 16
	s_cselect_b32 s65, s69, s65
	s_cmp_ge_u32 s74, 16
	s_cselect_b32 s66, s70, s66
	s_cmp_ge_u32 s75, 16
	s_cselect_b32 s67, s71, s67
	s_or_b32 s68, s64, 0x200
	s_or_b32 s69, s65, 0x200
	s_or_b32 s70, s66, 0x200
	s_or_b32 s71, s67, 0x200
	v_cmp_le_u32_e64 s[76:77], s68, v17
	v_cmp_le_u32_e64 s[78:79], s69, v18
	v_cmp_le_u32_e64 s[80:81], s70, v19
	v_cmp_le_u32_e64 s[82:83], s71, v20
	s_bcnt1_i32_b64 s72, s[76:77]
	s_bcnt1_i32_b64 s73, s[78:79]
	s_bcnt1_i32_b64 s74, s[80:81]
	s_bcnt1_i32_b64 s75, s[82:83]
	s_cmp_ge_u32 s72, 16
	s_cselect_b32 s64, s68, s64
	s_cmp_ge_u32 s73, 16
	s_cselect_b32 s65, s69, s65
	s_cmp_ge_u32 s74, 16
	s_cselect_b32 s66, s70, s66
	s_cmp_ge_u32 s75, 16
	s_cselect_b32 s67, s71, s67
	s_or_b32 s68, s64, 0x100
	s_or_b32 s69, s65, 0x100
	s_or_b32 s70, s66, 0x100
	s_or_b32 s71, s67, 0x100
	v_cmp_le_u32_e64 s[76:77], s68, v17
	v_cmp_le_u32_e64 s[78:79], s69, v18
	v_cmp_le_u32_e64 s[80:81], s70, v19
	v_cmp_le_u32_e64 s[82:83], s71, v20
	s_bcnt1_i32_b64 s72, s[76:77]
	s_bcnt1_i32_b64 s73, s[78:79]
	s_bcnt1_i32_b64 s74, s[80:81]
	s_bcnt1_i32_b64 s75, s[82:83]
	s_cmp_ge_u32 s72, 16
	s_cselect_b32 s64, s68, s64
	s_cmp_ge_u32 s73, 16
	s_cselect_b32 s65, s69, s65
	s_cmp_ge_u32 s74, 16
	s_cselect_b32 s66, s70, s66
	s_cmp_ge_u32 s75, 16
	s_cselect_b32 s67, s71, s67
	s_or_b32 s68, s64, 0x80
	s_or_b32 s69, s65, 0x80
	s_or_b32 s70, s66, 0x80
	s_or_b32 s71, s67, 0x80
	v_cmp_le_u32_e64 s[76:77], s68, v17
	v_cmp_le_u32_e64 s[78:79], s69, v18
	v_cmp_le_u32_e64 s[80:81], s70, v19
	v_cmp_le_u32_e64 s[82:83], s71, v20
	s_bcnt1_i32_b64 s72, s[76:77]
	s_bcnt1_i32_b64 s73, s[78:79]
	s_bcnt1_i32_b64 s74, s[80:81]
	s_bcnt1_i32_b64 s75, s[82:83]
	s_cmp_ge_u32 s72, 16
	s_cselect_b32 s64, s68, s64
	s_cmp_ge_u32 s73, 16
	s_cselect_b32 s65, s69, s65
	s_cmp_ge_u32 s74, 16
	s_cselect_b32 s66, s70, s66
	s_cmp_ge_u32 s75, 16
	s_cselect_b32 s67, s71, s67
	s_or_b32 s68, s64, 0x40
	s_or_b32 s69, s65, 0x40
	s_or_b32 s70, s66, 0x40
	s_or_b32 s71, s67, 0x40
	v_cmp_le_u32_e64 s[76:77], s68, v17
	v_cmp_le_u32_e64 s[78:79], s69, v18
	v_cmp_le_u32_e64 s[80:81], s70, v19
	v_cmp_le_u32_e64 s[82:83], s71, v20
	s_bcnt1_i32_b64 s72, s[76:77]
	s_bcnt1_i32_b64 s73, s[78:79]
	s_bcnt1_i32_b64 s74, s[80:81]
	s_bcnt1_i32_b64 s75, s[82:83]
	s_cmp_ge_u32 s72, 16
	s_cselect_b32 s64, s68, s64
	s_cmp_ge_u32 s73, 16
	s_cselect_b32 s65, s69, s65
	s_cmp_ge_u32 s74, 16
	s_cselect_b32 s66, s70, s66
	s_cmp_ge_u32 s75, 16
	s_cselect_b32 s67, s71, s67
	s_or_b32 s68, s64, 0x20
	s_or_b32 s69, s65, 0x20
	s_or_b32 s70, s66, 0x20
	s_or_b32 s71, s67, 0x20
	v_cmp_le_u32_e64 s[76:77], s68, v17
	v_cmp_le_u32_e64 s[78:79], s69, v18
	v_cmp_le_u32_e64 s[80:81], s70, v19
	v_cmp_le_u32_e64 s[82:83], s71, v20
	s_bcnt1_i32_b64 s72, s[76:77]
	s_bcnt1_i32_b64 s73, s[78:79]
	s_bcnt1_i32_b64 s74, s[80:81]
	s_bcnt1_i32_b64 s75, s[82:83]
	s_cmp_ge_u32 s72, 16
	s_cselect_b32 s64, s68, s64
	s_cmp_ge_u32 s73, 16
	s_cselect_b32 s65, s69, s65
	s_cmp_ge_u32 s74, 16
	s_cselect_b32 s66, s70, s66
	s_cmp_ge_u32 s75, 16
	s_cselect_b32 s67, s71, s67
	s_or_b32 s68, s64, 0x10
	s_or_b32 s69, s65, 0x10
	s_or_b32 s70, s66, 0x10
	s_or_b32 s71, s67, 0x10
	v_cmp_le_u32_e64 s[76:77], s68, v17
	v_cmp_le_u32_e64 s[78:79], s69, v18
	v_cmp_le_u32_e64 s[80:81], s70, v19
	v_cmp_le_u32_e64 s[82:83], s71, v20
	s_bcnt1_i32_b64 s72, s[76:77]
	s_bcnt1_i32_b64 s73, s[78:79]
	s_bcnt1_i32_b64 s74, s[80:81]
	s_bcnt1_i32_b64 s75, s[82:83]
	s_cmp_ge_u32 s72, 16
	s_cselect_b32 s64, s68, s64
	s_cmp_ge_u32 s73, 16
	s_cselect_b32 s65, s69, s65
	s_cmp_ge_u32 s74, 16
	s_cselect_b32 s66, s70, s66
	s_cmp_ge_u32 s75, 16
	s_cselect_b32 s67, s71, s67
	s_or_b32 s68, s64, 0x8
	s_or_b32 s69, s65, 0x8
	s_or_b32 s70, s66, 0x8
	s_or_b32 s71, s67, 0x8
	v_cmp_le_u32_e64 s[76:77], s68, v17
	v_cmp_le_u32_e64 s[78:79], s69, v18
	v_cmp_le_u32_e64 s[80:81], s70, v19
	v_cmp_le_u32_e64 s[82:83], s71, v20
	s_bcnt1_i32_b64 s72, s[76:77]
	s_bcnt1_i32_b64 s73, s[78:79]
	s_bcnt1_i32_b64 s74, s[80:81]
	s_bcnt1_i32_b64 s75, s[82:83]
	s_cmp_ge_u32 s72, 16
	s_cselect_b32 s64, s68, s64
	s_cmp_ge_u32 s73, 16
	s_cselect_b32 s65, s69, s65
	s_cmp_ge_u32 s74, 16
	s_cselect_b32 s66, s70, s66
	s_cmp_ge_u32 s75, 16
	s_cselect_b32 s67, s71, s67
	s_or_b32 s68, s64, 0x4
	s_or_b32 s69, s65, 0x4
	s_or_b32 s70, s66, 0x4
	s_or_b32 s71, s67, 0x4
	v_cmp_le_u32_e64 s[76:77], s68, v17
	v_cmp_le_u32_e64 s[78:79], s69, v18
	v_cmp_le_u32_e64 s[80:81], s70, v19
	v_cmp_le_u32_e64 s[82:83], s71, v20
	s_bcnt1_i32_b64 s72, s[76:77]
	s_bcnt1_i32_b64 s73, s[78:79]
	s_bcnt1_i32_b64 s74, s[80:81]
	s_bcnt1_i32_b64 s75, s[82:83]
	s_cmp_ge_u32 s72, 16
	s_cselect_b32 s64, s68, s64
	s_cmp_ge_u32 s73, 16
	s_cselect_b32 s65, s69, s65
	s_cmp_ge_u32 s74, 16
	s_cselect_b32 s66, s70, s66
	s_cmp_ge_u32 s75, 16
	s_cselect_b32 s67, s71, s67
	s_or_b32 s68, s64, 0x2
	s_or_b32 s69, s65, 0x2
	s_or_b32 s70, s66, 0x2
	s_or_b32 s71, s67, 0x2
	v_cmp_le_u32_e64 s[76:77], s68, v17
	v_cmp_le_u32_e64 s[78:79], s69, v18
	v_cmp_le_u32_e64 s[80:81], s70, v19
	v_cmp_le_u32_e64 s[82:83], s71, v20
	s_bcnt1_i32_b64 s72, s[76:77]
	s_bcnt1_i32_b64 s73, s[78:79]
	s_bcnt1_i32_b64 s74, s[80:81]
	s_bcnt1_i32_b64 s75, s[82:83]
	s_cmp_ge_u32 s72, 16
	s_cselect_b32 s64, s68, s64
	s_cmp_ge_u32 s73, 16
	s_cselect_b32 s65, s69, s65
	s_cmp_ge_u32 s74, 16
	s_cselect_b32 s66, s70, s66
	s_cmp_ge_u32 s75, 16
	s_cselect_b32 s67, s71, s67
	s_or_b32 s68, s64, 0x1
	s_or_b32 s69, s65, 0x1
	s_or_b32 s70, s66, 0x1
	s_or_b32 s71, s67, 0x1
	v_cmp_le_u32_e64 s[76:77], s68, v17
	v_cmp_le_u32_e64 s[78:79], s69, v18
	v_cmp_le_u32_e64 s[80:81], s70, v19
	v_cmp_le_u32_e64 s[82:83], s71, v20
	s_bcnt1_i32_b64 s72, s[76:77]
	s_bcnt1_i32_b64 s73, s[78:79]
	s_bcnt1_i32_b64 s74, s[80:81]
	s_bcnt1_i32_b64 s75, s[82:83]
	s_cmp_ge_u32 s72, 16
	s_cselect_b32 s64, s68, s64
	s_cmp_ge_u32 s73, 16
	s_cselect_b32 s65, s69, s65
	s_cmp_ge_u32 s74, 16
	s_cselect_b32 s66, s70, s66
	s_cmp_ge_u32 s75, 16
	s_cselect_b32 s67, s71, s67
	v_cmp_le_u32_e64 s[76:77], s64, v17
	s_bcnt1_i32_b64 s72, s[76:77]
	s_cmp_le_u32 s72, 16
	s_cbranch_scc1 .Lrk1q0_ok
	s_cmp_eq_u32 s64, 0xeb60d35
	s_cbranch_scc1 .Lrk1q0_ok
	v_cmp_lt_u32_e64 s[84:85], s64, v17
	v_cmp_eq_u32_e64 vcc, s64, v17
	s_bcnt1_i32_b64 s73, s[84:85]
	s_sub_i32 s73, 16, s73
.Lrk1q0_tie:
	s_bcnt1_i32_b64 s72, vcc
	s_cmp_le_u32 s72, s73
	s_cbranch_scc1 .Lrk1q0_tied
	s_flbit_i32_b64 s72, vcc
	s_sub_i32 s72, 63, s72
	s_bitset0_b64 vcc, s72
	s_branch .Lrk1q0_tie
.Lrk1q0_tied:
	s_or_b64 s[76:77], vcc, s[84:85]
.Lrk1q0_ok:
	v_cmp_le_u32_e64 s[78:79], s65, v18
	s_bcnt1_i32_b64 s72, s[78:79]
	s_cmp_le_u32 s72, 16
	s_cbranch_scc1 .Lrk1q1_ok
	s_cmp_eq_u32 s65, 0xeb60d35
	s_cbranch_scc1 .Lrk1q1_ok
	v_cmp_lt_u32_e64 s[84:85], s65, v18
	v_cmp_eq_u32_e64 vcc, s65, v18
	s_bcnt1_i32_b64 s73, s[84:85]
	s_sub_i32 s73, 16, s73

.Lrk1q1_tied:
	s_or_b64 s[78:79], vcc, s[84:85]
.Lrk1q1_ok:
	v_cmp_le_u32_e64 s[80:81], s66, v19
	s_bcnt1_i32_b64 s72, s[80:81]
	s_cmp_le_u32 s72, 16
	s_cbranch_scc1 .Lrk1q2_ok
	s_cmp_eq_u32 s66, 0xeb60d35
	s_cbranch_scc1 .Lrk1q2_ok
	v_cmp_lt_u32_e64 s[84:85], s66, v19
	v_cmp_eq_u32_e64 vcc, s66, v19
	s_bcnt1_i32_b64 s73, s[84:85]
	s_sub_i32 s73, 16, s73

.Lrk1q2_tied:
	s_or_b64 s[80:81], vcc, s[84:85]
.Lrk1q2_ok:
	v_cmp_le_u32_e64 s[82:83], s67, v20
	s_bcnt1_i32_b64 s72, s[82:83]
	s_cmp_le_u32 s72, 16
	s_cbranch_scc1 .Lrk1q3_ok
	s_cmp_eq_u32 s67, 0xeb60d35
	s_cbranch_scc1 .Lrk1q3_ok
	v_cmp_lt_u32_e64 s[84:85], s67, v20
	v_cmp_eq_u32_e64 vcc, s67, v20
	s_bcnt1_i32_b64 s73, s[84:85]
	s_sub_i32 s73, 16, s73

.Lrk1q3_tied:
	s_or_b64 s[82:83], vcc, s[84:85]
.Lrk1q3_ok:
	s_movk_i32 s84, 0x0
	v_cmp_eq_u32_e64 s[86:87], s84, v173
	s_movk_i32 s84, 0x100
	v_cmp_eq_u32_e64 s[88:89], s84, v173
	s_movk_i32 s84, 0x200
	v_cmp_eq_u32_e64 s[90:91], s84, v173
	s_movk_i32 s84, 0x300
	v_cmp_eq_u32_e64 s[92:93], s84, v173
	v_mov_b32_e32 v17, s77
	v_mov_b32_e32 v18, s76
	v_cndmask_b32_e64 v73, v73, v17, s[86:87]
	v_cndmask_b32_e64 v72, v72, v18, s[86:87]
	v_mov_b32_e32 v17, s79
	v_mov_b32_e32 v18, s78
	v_cndmask_b32_e64 v73, v73, v17, s[88:89]
	v_cndmask_b32_e64 v72, v72, v18, s[88:89]
	v_mov_b32_e32 v17, s81
	v_mov_b32_e32 v18, s80
	v_cndmask_b32_e64 v73, v73, v17, s[90:91]
	v_cndmask_b32_e64 v72, v72, v18, s[90:91]
	v_mov_b32_e32 v17, s83
	v_mov_b32_e32 v18, s82
	v_cndmask_b32_e64 v73, v73, v17, s[92:93]
	v_cndmask_b32_e64 v72, v72, v18, s[92:93]
.LBB0_860:
	v_readlane_b32 s42, v248, 27
	s_lshl_b32 s43, s42, 5
	v_readlane_b32 s42, v248, 24
	s_sub_i32 s42, s42, s43
	s_add_i32 s44, s42, 0xfe4
	v_mov_b64_e32 v[74:75], 0
	s_mov_b32 s46, 0
	s_mov_b32 s48, 0x9c10
	v_writelane_b32 v248, s43, 27
	v_mov_b32_e32 v20, 0
	v_mov_b32_e32 v19, 0
	s_and_saveexec_b64 s[42:43], s[38:39]
	ds_read_b32 v20, v16 offset:38656
	s_mov_b64 exec, s[42:43]
	s_and_saveexec_b64 s[42:43], s[2:3]
	ds_read_b32 v19, v16 offset:40732
	s_mov_b64 exec, s[42:43]
	s_add_i32 s84, s44, 3
	s_waitcnt lgkmcnt(0)
	v_add_f32_e32 v20, v20, v19
	v_cmp_ge_u32_e32 vcc, s84, v165
	v_cndmask_b32_e64 v20, v20, v180, s[40:41]
	s_nop 1
	v_cndmask_b32_e32 v20, v181, v20, vcc
	v_ashrrev_i32_e32 v19, 31, v20
	v_or_b32_e32 v19, 0x80000000, v19
	v_xor_b32_e32 v20, v19, v20
	v_mov_b32_e32 v19, 0
	v_mov_b32_e32 v18, 0
	s_and_saveexec_b64 s[42:43], s[38:39]
	ds_read_b32 v19, v16 offset:38400
	s_mov_b64 exec, s[42:43]
	s_and_saveexec_b64 s[42:43], s[2:3]
	ds_read_b32 v18, v16 offset:40472
	s_mov_b64 exec, s[42:43]
	s_add_i32 s84, s44, 2
	s_waitcnt lgkmcnt(0)
	v_add_f32_e32 v19, v19, v18
	v_cmp_ge_u32_e32 vcc, s84, v165
	v_cndmask_b32_e64 v19, v19, v180, s[40:41]
	s_nop 1
	v_cndmask_b32_e32 v19, v181, v19, vcc
	v_ashrrev_i32_e32 v18, 31, v19
	v_or_b32_e32 v18, 0x80000000, v18
	v_xor_b32_e32 v19, v18, v19
	v_mov_b32_e32 v18, 0
	v_mov_b32_e32 v17, 0
	s_and_saveexec_b64 s[42:43], s[38:39]
	ds_read_b32 v18, v16 offset:38144
	s_mov_b64 exec, s[42:43]
	s_and_saveexec_b64 s[42:43], s[2:3]
	ds_read_b32 v17, v16 offset:40212
	s_mov_b64 exec, s[42:43]
	s_add_i32 s84, s44, 1
	s_waitcnt lgkmcnt(0)
	v_add_f32_e32 v18, v18, v17
	v_cmp_ge_u32_e32 vcc, s84, v165
	v_cndmask_b32_e64 v18, v18, v180, s[40:41]
	s_nop 1
	v_cndmask_b32_e32 v18, v181, v18, vcc
	v_ashrrev_i32_e32 v17, 31, v18
	v_or_b32_e32 v17, 0x80000000, v17
	v_xor_b32_e32 v18, v17, v18
	v_mov_b32_e32 v17, 0
	v_mov_b32_e32 v75, 0
	s_and_saveexec_b64 s[42:43], s[38:39]
	ds_read_b32 v17, v16 offset:37888
	s_mov_b64 exec, s[42:43]
	s_and_saveexec_b64 s[42:43], s[2:3]
	ds_read_b32 v75, v16 offset:39952
	s_mov_b64 exec, s[42:43]
	s_add_i32 s84, s44, 0
	s_waitcnt lgkmcnt(0)
	v_add_f32_e32 v17, v17, v75
	v_cmp_ge_u32_e32 vcc, s84, v165
	v_cndmask_b32_e64 v17, v17, v180, s[40:41]
	s_nop 1
	v_cndmask_b32_e32 v17, v181, v17, vcc
	v_ashrrev_i32_e32 v75, 31, v17
	v_or_b32_e32 v75, 0x80000000, v75
	v_xor_b32_e32 v17, v75, v17
	v_mov_b32_e32 v75, 0
	s_add_i32 s44, s44, 4
	s_mov_b32 s64, 0
	s_mov_b32 s65, 0
	s_mov_b32 s66, 0
	s_mov_b32 s67, 0
	s_or_b32 s68, s64, 0x80000000
	s_or_b32 s69, s65, 0x80000000
	s_or_b32 s70, s66, 0x80000000
	s_or_b32 s71, s67, 0x80000000
	v_cmp_le_u32_e64 s[76:77], s68, v17
	v_cmp_le_u32_e64 s[78:79], s69, v18
	v_cmp_le_u32_e64 s[80:81], s70, v19
	v_cmp_le_u32_e64 s[82:83], s71, v20
	s_bcnt1_i32_b64 s72, s[76:77]
	s_bcnt1_i32_b64 s73, s[78:79]
	s_bcnt1_i32_b64 s74, s[80:81]
	s_bcnt1_i32_b64 s75, s[82:83]
	s_cmp_ge_u32 s72, 16
	s_cselect_b32 s64, s68, s64
	s_cmp_ge_u32 s73, 16
	s_cselect_b32 s65, s69, s65
	s_cmp_ge_u32 s74, 16
	s_cselect_b32 s66, s70, s66
	s_cmp_ge_u32 s75, 16
	s_cselect_b32 s67, s71, s67
	s_or_b32 s68, s64, 0x40000000
	s_or_b32 s69, s65, 0x40000000
	s_or_b32 s70, s66, 0x40000000
	s_or_b32 s71, s67, 0x40000000
	v_cmp_le_u32_e64 s[76:77], s68, v17
	v_cmp_le_u32_e64 s[78:79], s69, v18
	v_cmp_le_u32_e64 s[80:81], s70, v19
	v_cmp_le_u32_e64 s[82:83], s71, v20
	s_bcnt1_i32_b64 s72, s[76:77]
	s_bcnt1_i32_b64 s73, s[78:79]
	s_bcnt1_i32_b64 s74, s[80:81]
	s_bcnt1_i32_b64 s75, s[82:83]
	s_cmp_ge_u32 s72, 16
	s_cselect_b32 s64, s68, s64
	s_cmp_ge_u32 s73, 16
	s_cselect_b32 s65, s69, s65
	s_cmp_ge_u32 s74, 16
	s_cselect_b32 s66, s70, s66
	s_cmp_ge_u32 s75, 16
	s_cselect_b32 s67, s71, s67
	s_or_b32 s68, s64, 0x20000000
	s_or_b32 s69, s65, 0x20000000
	s_or_b32 s70, s66, 0x20000000
	s_or_b32 s71, s67, 0x20000000
	v_cmp_le_u32_e64 s[76:77], s68, v17
	v_cmp_le_u32_e64 s[78:79], s69, v18
	v_cmp_le_u32_e64 s[80:81], s70, v19
	v_cmp_le_u32_e64 s[82:83], s71, v20
	s_bcnt1_i32_b64 s72, s[76:77]
	s_bcnt1_i32_b64 s73, s[78:79]
	s_bcnt1_i32_b64 s74, s[80:81]
	s_bcnt1_i32_b64 s75, s[82:83]
	s_cmp_ge_u32 s72, 16
	s_cselect_b32 s64, s68, s64
	s_cmp_ge_u32 s73, 16
	s_cselect_b32 s65, s69, s65
	s_cmp_ge_u32 s74, 16
	s_cselect_b32 s66, s70, s66
	s_cmp_ge_u32 s75, 16
	s_cselect_b32 s67, s71, s67
	s_or_b32 s68, s64, 0x10000000
	s_or_b32 s69, s65, 0x10000000
	s_or_b32 s70, s66, 0x10000000
	s_or_b32 s71, s67, 0x10000000
	v_cmp_le_u32_e64 s[76:77], s68, v17
	v_cmp_le_u32_e64 s[78:79], s69, v18
	v_cmp_le_u32_e64 s[80:81], s70, v19
	v_cmp_le_u32_e64 s[82:83], s71, v20
	s_bcnt1_i32_b64 s72, s[76:77]
	s_bcnt1_i32_b64 s73, s[78:79]
	s_bcnt1_i32_b64 s74, s[80:81]
	s_bcnt1_i32_b64 s75, s[82:83]
	s_cmp_ge_u32 s72, 16
	s_cselect_b32 s64, s68, s64
	s_cmp_ge_u32 s73, 16
	s_cselect_b32 s65, s69, s65
	s_cmp_ge_u32 s74, 16
	s_cselect_b32 s66, s70, s66
	s_cmp_ge_u32 s75, 16
	s_cselect_b32 s67, s71, s67
	s_or_b32 s68, s64, 0x8000000
	s_or_b32 s69, s65, 0x8000000
	s_or_b32 s70, s66, 0x8000000
	s_or_b32 s71, s67, 0x8000000
	v_cmp_le_u32_e64 s[76:77], s68, v17
	v_cmp_le_u32_e64 s[78:79], s69, v18
	v_cmp_le_u32_e64 s[80:81], s70, v19
	v_cmp_le_u32_e64 s[82:83], s71, v20
	s_bcnt1_i32_b64 s72, s[76:77]
	s_bcnt1_i32_b64 s73, s[78:79]
	s_bcnt1_i32_b64 s74, s[80:81]
	s_bcnt1_i32_b64 s75, s[82:83]
	s_cmp_ge_u32 s72, 16
	s_cselect_b32 s64, s68, s64
	s_cmp_ge_u32 s73, 16
	s_cselect_b32 s65, s69, s65
	s_cmp_ge_u32 s74, 16
	s_cselect_b32 s66, s70, s66
	s_cmp_ge_u32 s75, 16
	s_cselect_b32 s67, s71, s67
	s_or_b32 s68, s64, 0x4000000
	s_or_b32 s69, s65, 0x4000000
	s_or_b32 s70, s66, 0x4000000
	s_or_b32 s71, s67, 0x4000000
	v_cmp_le_u32_e64 s[76:77], s68, v17
	v_cmp_le_u32_e64 s[78:79], s69, v18
	v_cmp_le_u32_e64 s[80:81], s70, v19
	v_cmp_le_u32_e64 s[82:83], s71, v20
	s_bcnt1_i32_b64 s72, s[76:77]
	s_bcnt1_i32_b64 s73, s[78:79]
	s_bcnt1_i32_b64 s74, s[80:81]
	s_bcnt1_i32_b64 s75, s[82:83]
	s_cmp_ge_u32 s72, 16
	s_cselect_b32 s64, s68, s64
	s_cmp_ge_u32 s73, 16
	s_cselect_b32 s65, s69, s65
	s_cmp_ge_u32 s74, 16
	s_cselect_b32 s66, s70, s66
	s_cmp_ge_u32 s75, 16
	s_cselect_b32 s67, s71, s67
	s_or_b32 s68, s64, 0x2000000
	s_or_b32 s69, s65, 0x2000000
	s_or_b32 s70, s66, 0x2000000
	s_or_b32 s71, s67, 0x2000000
	v_cmp_le_u32_e64 s[76:77], s68, v17
	v_cmp_le_u32_e64 s[78:79], s69, v18
	v_cmp_le_u32_e64 s[80:81], s70, v19
	v_cmp_le_u32_e64 s[82:83], s71, v20
	s_bcnt1_i32_b64 s72, s[76:77]
	s_bcnt1_i32_b64 s73, s[78:79]
	s_bcnt1_i32_b64 s74, s[80:81]
	s_bcnt1_i32_b64 s75, s[82:83]
	s_cmp_ge_u32 s72, 16
	s_cselect_b32 s64, s68, s64
	s_cmp_ge_u32 s73, 16
	s_cselect_b32 s65, s69, s65
	s_cmp_ge_u32 s74, 16
	s_cselect_b32 s66, s70, s66
	s_cmp_ge_u32 s75, 16
	s_cselect_b32 s67, s71, s67
	s_or_b32 s68, s64, 0x1000000
	s_or_b32 s69, s65, 0x1000000
	s_or_b32 s70, s66, 0x1000000
	s_or_b32 s71, s67, 0x1000000
	v_cmp_le_u32_e64 s[76:77], s68, v17
	v_cmp_le_u32_e64 s[78:79], s69, v18
	v_cmp_le_u32_e64 s[80:81], s70, v19
	v_cmp_le_u32_e64 s[82:83], s71, v20
	s_bcnt1_i32_b64 s72, s[76:77]
	s_bcnt1_i32_b64 s73, s[78:79]
	s_bcnt1_i32_b64 s74, s[80:81]
	s_bcnt1_i32_b64 s75, s[82:83]
	s_cmp_ge_u32 s72, 16
	s_cselect_b32 s64, s68, s64
	s_cmp_ge_u32 s73, 16
	s_cselect_b32 s65, s69, s65
	s_cmp_ge_u32 s74, 16
	s_cselect_b32 s66, s70, s66
	s_cmp_ge_u32 s75, 16
	s_cselect_b32 s67, s71, s67
	s_or_b32 s68, s64, 0x800000
	s_or_b32 s69, s65, 0x800000
	s_or_b32 s70, s66, 0x800000
	s_or_b32 s71, s67, 0x800000
	v_cmp_le_u32_e64 s[76:77], s68, v17
	v_cmp_le_u32_e64 s[78:79], s69, v18
	v_cmp_le_u32_e64 s[80:81], s70, v19
	v_cmp_le_u32_e64 s[82:83], s71, v20
	s_bcnt1_i32_b64 s72, s[76:77]
	s_bcnt1_i32_b64 s73, s[78:79]
	s_bcnt1_i32_b64 s74, s[80:81]
	s_bcnt1_i32_b64 s75, s[82:83]
	s_cmp_ge_u32 s72, 16
	s_cselect_b32 s64, s68, s64
	s_cmp_ge_u32 s73, 16
	s_cselect_b32 s65, s69, s65
	s_cmp_ge_u32 s74, 16
	s_cselect_b32 s66, s70, s66
	s_cmp_ge_u32 s75, 16
	s_cselect_b32 s67, s71, s67
	s_or_b32 s68, s64, 0x400000
	s_or_b32 s69, s65, 0x400000
	s_or_b32 s70, s66, 0x400000
	s_or_b32 s71, s67, 0x400000
	v_cmp_le_u32_e64 s[76:77], s68, v17
	v_cmp_le_u32_e64 s[78:79], s69, v18
	v_cmp_le_u32_e64 s[80:81], s70, v19
	v_cmp_le_u32_e64 s[82:83], s71, v20
	s_bcnt1_i32_b64 s72, s[76:77]
	s_bcnt1_i32_b64 s73, s[78:79]
	s_bcnt1_i32_b64 s74, s[80:81]
	s_bcnt1_i32_b64 s75, s[82:83]
	s_cmp_ge_u32 s72, 16
	s_cselect_b32 s64, s68, s64
	s_cmp_ge_u32 s73, 16
	s_cselect_b32 s65, s69, s65
	s_cmp_ge_u32 s74, 16
	s_cselect_b32 s66, s70, s66
	s_cmp_ge_u32 s75, 16
	s_cselect_b32 s67, s71, s67
	s_or_b32 s68, s64, 0x200000
	s_or_b32 s69, s65, 0x200000
	s_or_b32 s70, s66, 0x200000
	s_or_b32 s71, s67, 0x200000
	v_cmp_le_u32_e64 s[76:77], s68, v17
	v_cmp_le_u32_e64 s[78:79], s69, v18
	v_cmp_le_u32_e64 s[80:81], s70, v19
	v_cmp_le_u32_e64 s[82:83], s71, v20
	s_bcnt1_i32_b64 s72, s[76:77]
	s_bcnt1_i32_b64 s73, s[78:79]
	s_bcnt1_i32_b64 s74, s[80:81]
	s_bcnt1_i32_b64 s75, s[82:83]
	s_cmp_ge_u32 s72, 16
	s_cselect_b32 s64, s68, s64
	s_cmp_ge_u32 s73, 16
	s_cselect_b32 s65, s69, s65
	s_cmp_ge_u32 s74, 16
	s_cselect_b32 s66, s70, s66
	s_cmp_ge_u32 s75, 16
	s_cselect_b32 s67, s71, s67
	s_or_b32 s68, s64, 0x100000
	s_or_b32 s69, s65, 0x100000
	s_or_b32 s70, s66, 0x100000
	s_or_b32 s71, s67, 0x100000
	v_cmp_le_u32_e64 s[76:77], s68, v17
	v_cmp_le_u32_e64 s[78:79], s69, v18
	v_cmp_le_u32_e64 s[80:81], s70, v19
	v_cmp_le_u32_e64 s[82:83], s71, v20
	s_bcnt1_i32_b64 s72, s[76:77]
	s_bcnt1_i32_b64 s73, s[78:79]
	s_bcnt1_i32_b64 s74, s[80:81]
	s_bcnt1_i32_b64 s75, s[82:83]
	s_cmp_ge_u32 s72, 16
	s_cselect_b32 s64, s68, s64
	s_cmp_ge_u32 s73, 16
	s_cselect_b32 s65, s69, s65
	s_cmp_ge_u32 s74, 16
	s_cselect_b32 s66, s70, s66
	s_cmp_ge_u32 s75, 16
	s_cselect_b32 s67, s71, s67
	s_or_b32 s68, s64, 0x80000
	s_or_b32 s69, s65, 0x80000
	s_or_b32 s70, s66, 0x80000
	s_or_b32 s71, s67, 0x80000
	v_cmp_le_u32_e64 s[76:77], s68, v17
	v_cmp_le_u32_e64 s[78:79], s69, v18
	v_cmp_le_u32_e64 s[80:81], s70, v19
	v_cmp_le_u32_e64 s[82:83], s71, v20
	s_bcnt1_i32_b64 s72, s[76:77]
	s_bcnt1_i32_b64 s73, s[78:79]
	s_bcnt1_i32_b64 s74, s[80:81]
	s_bcnt1_i32_b64 s75, s[82:83]
	s_cmp_ge_u32 s72, 16
	s_cselect_b32 s64, s68, s64
	s_cmp_ge_u32 s73, 16
	s_cselect_b32 s65, s69, s65
	s_cmp_ge_u32 s74, 16
	s_cselect_b32 s66, s70, s66
	s_cmp_ge_u32 s75, 16
	s_cselect_b32 s67, s71, s67
	s_or_b32 s68, s64, 0x40000
	s_or_b32 s69, s65, 0x40000
	s_or_b32 s70, s66, 0x40000
	s_or_b32 s71, s67, 0x40000
	v_cmp_le_u32_e64 s[76:77], s68, v17
	v_cmp_le_u32_e64 s[78:79], s69, v18
	v_cmp_le_u32_e64 s[80:81], s70, v19
	v_cmp_le_u32_e64 s[82:83], s71, v20
	s_bcnt1_i32_b64 s72, s[76:77]
	s_bcnt1_i32_b64 s73, s[78:79]
	s_bcnt1_i32_b64 s74, s[80:81]
	s_bcnt1_i32_b64 s75, s[82:83]
	s_cmp_ge_u32 s72, 16
	s_cselect_b32 s64, s68, s64
	s_cmp_ge_u32 s73, 16
	s_cselect_b32 s65, s69, s65
	s_cmp_ge_u32 s74, 16
	s_cselect_b32 s66, s70, s66
	s_cmp_ge_u32 s75, 16
	s_cselect_b32 s67, s71, s67
	s_or_b32 s68, s64, 0x20000
	s_or_b32 s69, s65, 0x20000
	s_or_b32 s70, s66, 0x20000
	s_or_b32 s71, s67, 0x20000
	v_cmp_le_u32_e64 s[76:77], s68, v17
	v_cmp_le_u32_e64 s[78:79], s69, v18
	v_cmp_le_u32_e64 s[80:81], s70, v19
	v_cmp_le_u32_e64 s[82:83], s71, v20
	s_bcnt1_i32_b64 s72, s[76:77]
	s_bcnt1_i32_b64 s73, s[78:79]
	s_bcnt1_i32_b64 s74, s[80:81]
	s_bcnt1_i32_b64 s75, s[82:83]
	s_cmp_ge_u32 s72, 16
	s_cselect_b32 s64, s68, s64
	s_cmp_ge_u32 s73, 16
	s_cselect_b32 s65, s69, s65
	s_cmp_ge_u32 s74, 16
	s_cselect_b32 s66, s70, s66
	s_cmp_ge_u32 s75, 16
	s_cselect_b32 s67, s71, s67
	s_or_b32 s68, s64, 0x10000
	s_or_b32 s69, s65, 0x10000
	s_or_b32 s70, s66, 0x10000
	s_or_b32 s71, s67, 0x10000
	v_cmp_le_u32_e64 s[76:77], s68, v17
	v_cmp_le_u32_e64 s[78:79], s69, v18
	v_cmp_le_u32_e64 s[80:81], s70, v19
	v_cmp_le_u32_e64 s[82:83], s71, v20
	s_bcnt1_i32_b64 s72, s[76:77]
	s_bcnt1_i32_b64 s73, s[78:79]
	s_bcnt1_i32_b64 s74, s[80:81]
	s_bcnt1_i32_b64 s75, s[82:83]
	s_cmp_ge_u32 s72, 16
	s_cselect_b32 s64, s68, s64
	s_cmp_ge_u32 s73, 16
	s_cselect_b32 s65, s69, s65
	s_cmp_ge_u32 s74, 16
	s_cselect_b32 s66, s70, s66
	s_cmp_ge_u32 s75, 16
	s_cselect_b32 s67, s71, s67
	s_or_b32 s68, s64, 0x8000
	s_or_b32 s69, s65, 0x8000
	s_or_b32 s70, s66, 0x8000
	s_or_b32 s71, s67, 0x8000
	v_cmp_le_u32_e64 s[76:77], s68, v17
	v_cmp_le_u32_e64 s[78:79], s69, v18
	v_cmp_le_u32_e64 s[80:81], s70, v19
	v_cmp_le_u32_e64 s[82:83], s71, v20
	s_bcnt1_i32_b64 s72, s[76:77]
	s_bcnt1_i32_b64 s73, s[78:79]
	s_bcnt1_i32_b64 s74, s[80:81]
	s_bcnt1_i32_b64 s75, s[82:83]
	s_cmp_ge_u32 s72, 16
	s_cselect_b32 s64, s68, s64
	s_cmp_ge_u32 s73, 16
	s_cselect_b32 s65, s69, s65
	s_cmp_ge_u32 s74, 16
	s_cselect_b32 s66, s70, s66
	s_cmp_ge_u32 s75, 16
	s_cselect_b32 s67, s71, s67
	s_or_b32 s68, s64, 0x4000
	s_or_b32 s69, s65, 0x4000
	s_or_b32 s70, s66, 0x4000
	s_or_b32 s71, s67, 0x4000
	v_cmp_le_u32_e64 s[76:77], s68, v17
	v_cmp_le_u32_e64 s[78:79], s69, v18
	v_cmp_le_u32_e64 s[80:81], s70, v19
	v_cmp_le_u32_e64 s[82:83], s71, v20
	s_bcnt1_i32_b64 s72, s[76:77]
	s_bcnt1_i32_b64 s73, s[78:79]
	s_bcnt1_i32_b64 s74, s[80:81]
	s_bcnt1_i32_b64 s75, s[82:83]
	s_cmp_ge_u32 s72, 16
	s_cselect_b32 s64, s68, s64
	s_cmp_ge_u32 s73, 16
	s_cselect_b32 s65, s69, s65
	s_cmp_ge_u32 s74, 16
	s_cselect_b32 s66, s70, s66
	s_cmp_ge_u32 s75, 16
	s_cselect_b32 s67, s71, s67
	s_or_b32 s68, s64, 0x2000
	s_or_b32 s69, s65, 0x2000
	s_or_b32 s70, s66, 0x2000
	s_or_b32 s71, s67, 0x2000
	v_cmp_le_u32_e64 s[76:77], s68, v17
	v_cmp_le_u32_e64 s[78:79], s69, v18
	v_cmp_le_u32_e64 s[80:81], s70, v19
	v_cmp_le_u32_e64 s[82:83], s71, v20
	s_bcnt1_i32_b64 s72, s[76:77]
	s_bcnt1_i32_b64 s73, s[78:79]
	s_bcnt1_i32_b64 s74, s[80:81]
	s_bcnt1_i32_b64 s75, s[82:83]
	s_cmp_ge_u32 s72, 16
	s_cselect_b32 s64, s68, s64
	s_cmp_ge_u32 s73, 16
	s_cselect_b32 s65, s69, s65
	s_cmp_ge_u32 s74, 16
	s_cselect_b32 s66, s70, s66
	s_cmp_ge_u32 s75, 16
	s_cselect_b32 s67, s71, s67
	s_or_b32 s68, s64, 0x1000
	s_or_b32 s69, s65, 0x1000
	s_or_b32 s70, s66, 0x1000
	s_or_b32 s71, s67, 0x1000
	v_cmp_le_u32_e64 s[76:77], s68, v17
	v_cmp_le_u32_e64 s[78:79], s69, v18
	v_cmp_le_u32_e64 s[80:81], s70, v19
	v_cmp_le_u32_e64 s[82:83], s71, v20
	s_bcnt1_i32_b64 s72, s[76:77]
	s_bcnt1_i32_b64 s73, s[78:79]
	s_bcnt1_i32_b64 s74, s[80:81]
	s_bcnt1_i32_b64 s75, s[82:83]
	s_cmp_ge_u32 s72, 16
	s_cselect_b32 s64, s68, s64
	s_cmp_ge_u32 s73, 16
	s_cselect_b32 s65, s69, s65
	s_cmp_ge_u32 s74, 16
	s_cselect_b32 s66, s70, s66
	s_cmp_ge_u32 s75, 16
	s_cselect_b32 s67, s71, s67
	s_or_b32 s68, s64, 0x800
	s_or_b32 s69, s65, 0x800
	s_or_b32 s70, s66, 0x800
	s_or_b32 s71, s67, 0x800
	v_cmp_le_u32_e64 s[76:77], s68, v17
	v_cmp_le_u32_e64 s[78:79], s69, v18
	v_cmp_le_u32_e64 s[80:81], s70, v19
	v_cmp_le_u32_e64 s[82:83], s71, v20
	s_bcnt1_i32_b64 s72, s[76:77]
	s_bcnt1_i32_b64 s73, s[78:79]
	s_bcnt1_i32_b64 s74, s[80:81]
	s_bcnt1_i32_b64 s75, s[82:83]
	s_cmp_ge_u32 s72, 16
	s_cselect_b32 s64, s68, s64
	s_cmp_ge_u32 s73, 16
	s_cselect_b32 s65, s69, s65
	s_cmp_ge_u32 s74, 16
	s_cselect_b32 s66, s70, s66
	s_cmp_ge_u32 s75, 16
	s_cselect_b32 s67, s71, s67
	s_or_b32 s68, s64, 0x400
	s_or_b32 s69, s65, 0x400
	s_or_b32 s70, s66, 0x400
	s_or_b32 s71, s67, 0x400
	v_cmp_le_u32_e64 s[76:77], s68, v17
	v_cmp_le_u32_e64 s[78:79], s69, v18
	v_cmp_le_u32_e64 s[80:81], s70, v19
	v_cmp_le_u32_e64 s[82:83], s71, v20
	s_bcnt1_i32_b64 s72, s[76:77]
	s_bcnt1_i32_b64 s73, s[78:79]
	s_bcnt1_i32_b64 s74, s[80:81]
	s_bcnt1_i32_b64 s75, s[82:83]
	s_cmp_ge_u32 s72, 16
	s_cselect_b32 s64, s68, s64
	s_cmp_ge_u32 s73, 16
	s_cselect_b32 s65, s69, s65
	s_cmp_ge_u32 s74, 16
	s_cselect_b32 s66, s70, s66
	s_cmp_ge_u32 s75, 16
	s_cselect_b32 s67, s71, s67
	s_or_b32 s68, s64, 0x200
	s_or_b32 s69, s65, 0x200
	s_or_b32 s70, s66, 0x200
	s_or_b32 s71, s67, 0x200
	v_cmp_le_u32_e64 s[76:77], s68, v17
	v_cmp_le_u32_e64 s[78:79], s69, v18
	v_cmp_le_u32_e64 s[80:81], s70, v19
	v_cmp_le_u32_e64 s[82:83], s71, v20
	s_bcnt1_i32_b64 s72, s[76:77]
	s_bcnt1_i32_b64 s73, s[78:79]
	s_bcnt1_i32_b64 s74, s[80:81]
	s_bcnt1_i32_b64 s75, s[82:83]
	s_cmp_ge_u32 s72, 16
	s_cselect_b32 s64, s68, s64
	s_cmp_ge_u32 s73, 16
	s_cselect_b32 s65, s69, s65
	s_cmp_ge_u32 s74, 16
	s_cselect_b32 s66, s70, s66
	s_cmp_ge_u32 s75, 16
	s_cselect_b32 s67, s71, s67
	s_or_b32 s68, s64, 0x100
	s_or_b32 s69, s65, 0x100
	s_or_b32 s70, s66, 0x100
	s_or_b32 s71, s67, 0x100
	v_cmp_le_u32_e64 s[76:77], s68, v17
	v_cmp_le_u32_e64 s[78:79], s69, v18
	v_cmp_le_u32_e64 s[80:81], s70, v19
	v_cmp_le_u32_e64 s[82:83], s71, v20
	s_bcnt1_i32_b64 s72, s[76:77]
	s_bcnt1_i32_b64 s73, s[78:79]
	s_bcnt1_i32_b64 s74, s[80:81]
	s_bcnt1_i32_b64 s75, s[82:83]
	s_cmp_ge_u32 s72, 16
	s_cselect_b32 s64, s68, s64
	s_cmp_ge_u32 s73, 16
	s_cselect_b32 s65, s69, s65
	s_cmp_ge_u32 s74, 16
	s_cselect_b32 s66, s70, s66
	s_cmp_ge_u32 s75, 16
	s_cselect_b32 s67, s71, s67
	s_or_b32 s68, s64, 0x80
	s_or_b32 s69, s65, 0x80
	s_or_b32 s70, s66, 0x80
	s_or_b32 s71, s67, 0x80
	v_cmp_le_u32_e64 s[76:77], s68, v17
	v_cmp_le_u32_e64 s[78:79], s69, v18
	v_cmp_le_u32_e64 s[80:81], s70, v19
	v_cmp_le_u32_e64 s[82:83], s71, v20
	s_bcnt1_i32_b64 s72, s[76:77]
	s_bcnt1_i32_b64 s73, s[78:79]
	s_bcnt1_i32_b64 s74, s[80:81]
	s_bcnt1_i32_b64 s75, s[82:83]
	s_cmp_ge_u32 s72, 16
	s_cselect_b32 s64, s68, s64
	s_cmp_ge_u32 s73, 16
	s_cselect_b32 s65, s69, s65
	s_cmp_ge_u32 s74, 16
	s_cselect_b32 s66, s70, s66
	s_cmp_ge_u32 s75, 16
	s_cselect_b32 s67, s71, s67
	s_or_b32 s68, s64, 0x40
	s_or_b32 s69, s65, 0x40
	s_or_b32 s70, s66, 0x40
	s_or_b32 s71, s67, 0x40
	v_cmp_le_u32_e64 s[76:77], s68, v17
	v_cmp_le_u32_e64 s[78:79], s69, v18
	v_cmp_le_u32_e64 s[80:81], s70, v19
	v_cmp_le_u32_e64 s[82:83], s71, v20
	s_bcnt1_i32_b64 s72, s[76:77]
	s_bcnt1_i32_b64 s73, s[78:79]
	s_bcnt1_i32_b64 s74, s[80:81]
	s_bcnt1_i32_b64 s75, s[82:83]
	s_cmp_ge_u32 s72, 16
	s_cselect_b32 s64, s68, s64
	s_cmp_ge_u32 s73, 16
	s_cselect_b32 s65, s69, s65
	s_cmp_ge_u32 s74, 16
	s_cselect_b32 s66, s70, s66
	s_cmp_ge_u32 s75, 16
	s_cselect_b32 s67, s71, s67
	s_or_b32 s68, s64, 0x20
	s_or_b32 s69, s65, 0x20
	s_or_b32 s70, s66, 0x20
	s_or_b32 s71, s67, 0x20
	v_cmp_le_u32_e64 s[76:77], s68, v17
	v_cmp_le_u32_e64 s[78:79], s69, v18
	v_cmp_le_u32_e64 s[80:81], s70, v19
	v_cmp_le_u32_e64 s[82:83], s71, v20
	s_bcnt1_i32_b64 s72, s[76:77]
	s_bcnt1_i32_b64 s73, s[78:79]
	s_bcnt1_i32_b64 s74, s[80:81]
	s_bcnt1_i32_b64 s75, s[82:83]
	s_cmp_ge_u32 s72, 16
	s_cselect_b32 s64, s68, s64
	s_cmp_ge_u32 s73, 16
	s_cselect_b32 s65, s69, s65
	s_cmp_ge_u32 s74, 16
	s_cselect_b32 s66, s70, s66
	s_cmp_ge_u32 s75, 16
	s_cselect_b32 s67, s71, s67
	s_or_b32 s68, s64, 0x10
	s_or_b32 s69, s65, 0x10
	s_or_b32 s70, s66, 0x10
	s_or_b32 s71, s67, 0x10
	v_cmp_le_u32_e64 s[76:77], s68, v17
	v_cmp_le_u32_e64 s[78:79], s69, v18
	v_cmp_le_u32_e64 s[80:81], s70, v19
	v_cmp_le_u32_e64 s[82:83], s71, v20
	s_bcnt1_i32_b64 s72, s[76:77]
	s_bcnt1_i32_b64 s73, s[78:79]
	s_bcnt1_i32_b64 s74, s[80:81]
	s_bcnt1_i32_b64 s75, s[82:83]
	s_cmp_ge_u32 s72, 16
	s_cselect_b32 s64, s68, s64
	s_cmp_ge_u32 s73, 16
	s_cselect_b32 s65, s69, s65
	s_cmp_ge_u32 s74, 16
	s_cselect_b32 s66, s70, s66
	s_cmp_ge_u32 s75, 16
	s_cselect_b32 s67, s71, s67
	s_or_b32 s68, s64, 0x8
	s_or_b32 s69, s65, 0x8
	s_or_b32 s70, s66, 0x8
	s_or_b32 s71, s67, 0x8
	v_cmp_le_u32_e64 s[76:77], s68, v17
	v_cmp_le_u32_e64 s[78:79], s69, v18
	v_cmp_le_u32_e64 s[80:81], s70, v19
	v_cmp_le_u32_e64 s[82:83], s71, v20
	s_bcnt1_i32_b64 s72, s[76:77]
	s_bcnt1_i32_b64 s73, s[78:79]
	s_bcnt1_i32_b64 s74, s[80:81]
	s_bcnt1_i32_b64 s75, s[82:83]
	s_cmp_ge_u32 s72, 16
	s_cselect_b32 s64, s68, s64
	s_cmp_ge_u32 s73, 16
	s_cselect_b32 s65, s69, s65
	s_cmp_ge_u32 s74, 16
	s_cselect_b32 s66, s70, s66
	s_cmp_ge_u32 s75, 16
	s_cselect_b32 s67, s71, s67
	s_or_b32 s68, s64, 0x4
	s_or_b32 s69, s65, 0x4
	s_or_b32 s70, s66, 0x4
	s_or_b32 s71, s67, 0x4
	v_cmp_le_u32_e64 s[76:77], s68, v17
	v_cmp_le_u32_e64 s[78:79], s69, v18
	v_cmp_le_u32_e64 s[80:81], s70, v19
	v_cmp_le_u32_e64 s[82:83], s71, v20
	s_bcnt1_i32_b64 s72, s[76:77]
	s_bcnt1_i32_b64 s73, s[78:79]
	s_bcnt1_i32_b64 s74, s[80:81]
	s_bcnt1_i32_b64 s75, s[82:83]
	s_cmp_ge_u32 s72, 16
	s_cselect_b32 s64, s68, s64
	s_cmp_ge_u32 s73, 16
	s_cselect_b32 s65, s69, s65
	s_cmp_ge_u32 s74, 16
	s_cselect_b32 s66, s70, s66
	s_cmp_ge_u32 s75, 16
	s_cselect_b32 s67, s71, s67
	s_or_b32 s68, s64, 0x2
	s_or_b32 s69, s65, 0x2
	s_or_b32 s70, s66, 0x2
	s_or_b32 s71, s67, 0x2
	v_cmp_le_u32_e64 s[76:77], s68, v17
	v_cmp_le_u32_e64 s[78:79], s69, v18
	v_cmp_le_u32_e64 s[80:81], s70, v19
	v_cmp_le_u32_e64 s[82:83], s71, v20
	s_bcnt1_i32_b64 s72, s[76:77]
	s_bcnt1_i32_b64 s73, s[78:79]
	s_bcnt1_i32_b64 s74, s[80:81]
	s_bcnt1_i32_b64 s75, s[82:83]
	s_cmp_ge_u32 s72, 16
	s_cselect_b32 s64, s68, s64
	s_cmp_ge_u32 s73, 16
	s_cselect_b32 s65, s69, s65
	s_cmp_ge_u32 s74, 16
	s_cselect_b32 s66, s70, s66
	s_cmp_ge_u32 s75, 16
	s_cselect_b32 s67, s71, s67
	s_or_b32 s68, s64, 0x1
	s_or_b32 s69, s65, 0x1
	s_or_b32 s70, s66, 0x1
	s_or_b32 s71, s67, 0x1
	v_cmp_le_u32_e64 s[76:77], s68, v17
	v_cmp_le_u32_e64 s[78:79], s69, v18
	v_cmp_le_u32_e64 s[80:81], s70, v19
	v_cmp_le_u32_e64 s[82:83], s71, v20
	s_bcnt1_i32_b64 s72, s[76:77]
	s_bcnt1_i32_b64 s73, s[78:79]
	s_bcnt1_i32_b64 s74, s[80:81]
	s_bcnt1_i32_b64 s75, s[82:83]
	s_cmp_ge_u32 s72, 16
	s_cselect_b32 s64, s68, s64
	s_cmp_ge_u32 s73, 16
	s_cselect_b32 s65, s69, s65
	s_cmp_ge_u32 s74, 16
	s_cselect_b32 s66, s70, s66
	s_cmp_ge_u32 s75, 16
	s_cselect_b32 s67, s71, s67
	v_cmp_le_u32_e64 s[76:77], s64, v17
	s_bcnt1_i32_b64 s72, s[76:77]
	s_cmp_le_u32 s72, 16
	s_cbranch_scc1 .Lrk2q0_ok
	s_cmp_eq_u32 s64, 0xeb60d35
	s_cbranch_scc1 .Lrk2q0_ok
	v_cmp_lt_u32_e64 s[84:85], s64, v17
	v_cmp_eq_u32_e64 vcc, s64, v17
	s_bcnt1_i32_b64 s73, s[84:85]
	s_sub_i32 s73, 16, s73

.Lrk2q3_ok:
	s_movk_i32 s84, 0x0
	v_cmp_eq_u32_e64 s[86:87], s84, v173
	s_movk_i32 s84, 0x100
	v_cmp_eq_u32_e64 s[88:89], s84, v173
	s_movk_i32 s84, 0x200
	v_cmp_eq_u32_e64 s[90:91], s84, v173
	s_movk_i32 s84, 0x300
	v_cmp_eq_u32_e64 s[92:93], s84, v173
	v_mov_b32_e32 v17, s77
	v_mov_b32_e32 v18, s76
	v_cndmask_b32_e64 v75, v75, v17, s[86:87]
	v_cndmask_b32_e64 v74, v74, v18, s[86:87]
	v_mov_b32_e32 v17, s79
	v_mov_b32_e32 v18, s78
	v_cndmask_b32_e64 v75, v75, v17, s[88:89]
	v_cndmask_b32_e64 v74, v74, v18, s[88:89]
	v_mov_b32_e32 v17, s81
	v_mov_b32_e32 v18, s80
	v_cndmask_b32_e64 v75, v75, v17, s[90:91]
	v_cndmask_b32_e64 v74, v74, v18, s[90:91]
	v_mov_b32_e32 v17, s83
	v_mov_b32_e32 v18, s82
	v_cndmask_b32_e64 v75, v75, v17, s[92:93]
	v_cndmask_b32_e64 v74, v74, v18, s[92:93]

.LBB0_912:
	s_or_b64 exec, exec, s[8:9]
	s_lshl_b32 s9, s0, 7
	s_lshl_b32 s0, s21, 7
	v_or_b32_e32 v0, s9, v214
	s_and_b32 s8, s0, 0x380
	v_lshlrev_b32_e32 v116, 11, v0
	v_lshl_add_u64 v[100:101], v[96:97], 0, v[116:117]
	v_or_b32_e32 v0, s8, v214
	v_lshlrev_b32_e32 v116, 11, v0
	v_add_co_u32_e32 v38, vcc, s16, v100
	v_lshl_add_u64 v[102:103], v[98:99], 0, v[116:117]
	s_nop 0
	v_addc_co_u32_e32 v39, vcc, 0, v101, vcc
	v_add_co_u32_e32 v40, vcc, s16, v102
	s_nop 1
	v_addc_co_u32_e32 v41, vcc, 0, v103, vcc
	v_add_co_u32_e32 v42, vcc, s17, v100
	s_barrier
	s_nop 0
	v_addc_co_u32_e32 v43, vcc, 0, v101, vcc
	v_add_co_u32_e32 v44, vcc, s17, v102
	s_nop 1
	v_addc_co_u32_e32 v45, vcc, 0, v103, vcc
	v_add_co_u32_e32 v46, vcc, s18, v100
	global_load_dwordx4 v[0:3], v[100:101], off
	global_load_dwordx4 v[4:7], v[102:103], off
	v_addc_co_u32_e32 v47, vcc, 0, v101, vcc
	v_add_co_u32_e32 v48, vcc, s18, v102
	global_load_dwordx4 v[8:11], v[38:39], off
	s_nop 0
	v_addc_co_u32_e32 v49, vcc, 0, v103, vcc
	global_load_dwordx4 v[16:19], v[40:41], off
	global_load_dwordx4 v[20:23], v[42:43], off
	global_load_dwordx4 v[24:27], v[44:45], off
	global_load_dwordx4 v[28:31], v[46:47], off
	global_load_dwordx4 v[34:37], v[48:49], off
	global_load_dwordx4 v[64:67], v[100:101], off offset:128
	global_load_dwordx4 v[68:71], v[102:103], off offset:128
	global_load_dwordx4 v[72:75], v[38:39], off offset:128
	global_load_dwordx4 v[80:83], v[42:43], off offset:128
	global_load_dwordx4 v[76:79], v[46:47], off offset:128
	global_load_dwordx4 v[84:87], v[40:41], off offset:128
	global_load_dwordx4 v[88:91], v[44:45], off offset:128
	global_load_dwordx4 v[92:95], v[48:49], off offset:128
	v_readfirstlane_b32 s0, v104
	s_and_b32 s10, s0, 64
	s_lshr_b32 s0, s0, 1
	s_and_b32 s12, s0, 0x7fffffc0
	v_or_b32_e32 v50, s10, v108
	v_mov_b32_e32 v12, 0
	v_or_b32_e32 v51, s12, v108
	v_mul_u32_u24_e32 v38, 0x48, v50
	s_mov_b32 s13, 0
	s_movk_i32 s11, 0x80
	v_mov_b32_e32 v13, v12
	v_mov_b32_e32 v14, v12
	v_mov_b32_e32 v15, v12
	v_mov_b32_e32 v32, v12
	v_mov_b32_e32 v33, v12
	v_lshl_add_u64 v[106:107], v[100:101], 0, s[2:3]
	v_lshl_add_u64 v[118:119], v[100:101], 0, s[4:5]
	v_lshl_add_u64 v[120:121], v[100:101], 0, s[6:7]
	v_mad_u64_u32 v[122:123], s[22:23], v51, s19, v[110:111]
	v_lshl_add_u32 v109, v38, 1, v110
	v_bfe_u32 v217, v108, 1, 3
	v_lshlrev_b32_e32 v217, 4, v217
	v_xor_b32_e32 v217, v217, v110
	v_or_b32_e32 v218, s12, v108
	v_lshl_add_u32 v122, v218, 7, v217
	v_xor_b32_e32 v218, 64, v122
	v_or_b32_e32 v219, s10, v108
	v_lshl_add_u32 v109, v219, 7, v217
	v_xor_b32_e32 v219, 64, v109
	v_lshl_add_u64 v[124:125], v[102:103], 0, s[2:3]
	v_lshl_add_u64 v[126:127], v[102:103], 0, s[4:5]
	v_lshl_add_u64 v[128:129], v[102:103], 0, s[6:7]
	v_mov_b32_e32 v52, v12
	v_mov_b32_e32 v53, v12
	v_mov_b32_e32 v54, v12
	v_mov_b32_e32 v55, v12
	v_mov_b32_e32 v56, v12
	v_mov_b32_e32 v57, v12
	v_mov_b32_e32 v58, v12
	v_mov_b32_e32 v59, v12
	v_mov_b32_e32 v38, v12
	v_mov_b32_e32 v39, v12
	v_mov_b32_e32 v40, v12
	v_mov_b32_e32 v41, v12
	v_mov_b32_e32 v42, v12
	v_mov_b32_e32 v43, v12
	v_mov_b32_e32 v44, v12
	v_mov_b32_e32 v45, v12
	v_mov_b32_e32 v46, v12
	v_mov_b32_e32 v47, v12
	v_mov_b32_e32 v48, v12
	v_mov_b32_e32 v49, v12
	v_mov_b32_e32 v50, v12
	v_mov_b32_e32 v51, v12
	s_waitcnt vmcnt(15)
	ds_write_b128 v215, v[0:3]
	s_waitcnt vmcnt(14)
	ds_write_b128 v215, v[4:7] offset:36864
	s_waitcnt vmcnt(13)
	ds_write_b128 v215, v[8:11] offset:4096
	s_waitcnt vmcnt(11)
	ds_write_b128 v215, v[20:23] offset:8192
	s_waitcnt vmcnt(9)
	ds_write_b128 v215, v[28:31] offset:12288
	ds_write_b128 v215, v[16:19] offset:40960
	ds_write_b128 v215, v[24:27] offset:45056
	s_waitcnt vmcnt(8)
	ds_write_b128 v215, v[34:37] offset:49152
	v_mov_b32_e32 v34, v12
	v_mov_b32_e32 v35, v12
	v_mov_b32_e32 v36, v12
	v_mov_b32_e32 v37, v12
	v_mov_b32_e32 v24, v12
	v_mov_b32_e32 v25, v12
	v_mov_b32_e32 v26, v12
	v_mov_b32_e32 v27, v12
	v_mov_b32_e32 v20, v12
	v_mov_b32_e32 v21, v12
	v_mov_b32_e32 v22, v12
	v_mov_b32_e32 v23, v12
	v_mov_b32_e32 v16, v12
	v_mov_b32_e32 v17, v12
	v_mov_b32_e32 v18, v12
	v_mov_b32_e32 v19, v12
	v_mov_b32_e32 v28, v12
	v_mov_b32_e32 v29, v12
	v_mov_b32_e32 v30, v12
	v_mov_b32_e32 v31, v12
	v_mov_b32_e32 v0, v12
	v_mov_b32_e32 v1, v12
	v_mov_b32_e32 v2, v12
	v_mov_b32_e32 v3, v12
	v_mov_b32_e32 v4, v12
	v_mov_b32_e32 v5, v12
	v_mov_b32_e32 v6, v12
	v_mov_b32_e32 v7, v12
	v_mov_b32_e32 v8, v12
	v_mov_b32_e32 v9, v12
	v_mov_b32_e32 v10, v12
	v_mov_b32_e32 v11, v12
	v_mov_b32_e32 v60, v12
	v_mov_b32_e32 v61, v12
	v_mov_b32_e32 v62, v12
	v_mov_b32_e32 v63, v12
	s_waitcnt lgkmcnt(0)
	s_barrier
.LBB0_913:
	ds_read_b128 v[130:133], v122
	ds_read_b128 v[134:137], v109 offset:36864
	ds_read_b128 v[138:141], v109 offset:38912
	ds_read_b128 v[142:145], v109 offset:40960
	ds_read_b128 v[146:149], v109 offset:43008
	s_add_i32 s21, s13, 2
	s_waitcnt lgkmcnt(3)
	v_mfma_f32_16x16x32_bf16 v[12:15], v[130:133], v[134:137], v[12:15]
	s_cmp_lt_u32 s13, 14
	s_cselect_b64 s[22:23], -1, 0
	s_and_b64 vcc, s[22:23], exec
	s_waitcnt lgkmcnt(2)
	v_mfma_f32_16x16x32_bf16 v[32:35], v[130:133], v[138:141], v[32:35]
	s_cselect_b32 s0, s11, 0x3c0
	s_lshl_b64 s[22:23], s[0:1], 1
	v_lshl_add_u64 v[162:163], v[106:107], 0, s[22:23]
	s_waitcnt lgkmcnt(1)
	v_mfma_f32_16x16x32_bf16 v[52:55], v[130:133], v[142:145], v[52:55]
	v_lshl_add_u64 v[166:167], v[118:119], 0, s[22:23]
	v_lshl_add_u64 v[158:159], v[102:103], 0, s[22:23]
	v_lshl_add_u64 v[170:171], v[128:129], 0, s[22:23]
	s_waitcnt lgkmcnt(0)
	v_mfma_f32_16x16x32_bf16 v[56:59], v[130:133], v[146:149], v[56:59]
	ds_read_b128 v[130:133], v122 offset:2048
	ds_read_b128 v[150:153], v122 offset:4096
	ds_read_b128 v[154:157], v122 offset:6144
	global_load_dwordx4 v[162:165], v[162:163], off
	s_waitcnt lgkmcnt(2)
	v_mfma_f32_16x16x32_bf16 v[36:39], v[130:133], v[134:137], v[36:39]
	global_load_dwordx4 v[158:161], v[158:159], off
	v_mfma_f32_16x16x32_bf16 v[40:43], v[130:133], v[138:141], v[40:43]
	v_mfma_f32_16x16x32_bf16 v[44:47], v[130:133], v[142:145], v[44:47]
	v_mfma_f32_16x16x32_bf16 v[48:51], v[130:133], v[146:149], v[48:51]
	v_lshl_add_u64 v[130:131], v[100:101], 0, s[22:23]
	global_load_dwordx4 v[130:133], v[130:131], off
	s_waitcnt lgkmcnt(1)
	v_mfma_f32_16x16x32_bf16 v[24:27], v[150:153], v[134:137], v[24:27]
	v_mfma_f32_16x16x32_bf16 v[20:23], v[150:153], v[138:141], v[20:23]
	v_mfma_f32_16x16x32_bf16 v[16:19], v[150:153], v[142:145], v[16:19]
	v_mfma_f32_16x16x32_bf16 v[28:31], v[150:153], v[146:149], v[28:31]
	v_lshl_add_u64 v[150:151], v[124:125], 0, s[22:23]
	global_load_dwordx4 v[150:153], v[150:151], off
	s_waitcnt lgkmcnt(0)
	v_mfma_f32_16x16x32_bf16 v[0:3], v[154:157], v[134:137], v[0:3]
	global_load_dwordx4 v[134:137], v[166:167], off
	v_lshl_add_u64 v[166:167], v[126:127], 0, s[22:23]
	global_load_dwordx4 v[166:169], v[166:167], off
	v_mfma_f32_16x16x32_bf16 v[4:7], v[154:157], v[138:141], v[4:7]
	v_lshl_add_u64 v[138:139], v[120:121], 0, s[22:23]
	global_load_dwordx4 v[138:141], v[138:139], off
	v_mfma_f32_16x16x32_bf16 v[8:11], v[154:157], v[142:145], v[8:11]
	global_load_dwordx4 v[142:145], v[170:171], off
	v_mfma_f32_16x16x32_bf16 v[60:63], v[154:157], v[146:149], v[60:63]
	ds_read_b128 v[146:149], v218
	ds_read_b128 v[154:157], v219 offset:36864
	ds_read_b128 v[170:173], v218 offset:2048
	ds_read_b128 v[174:177], v219 offset:38912
	ds_read_b128 v[178:181], v219 offset:40960
	ds_read_b128 v[182:185], v219 offset:43008
	s_min_u32 s0, s13, 12
	s_waitcnt lgkmcnt(4)
	v_mfma_f32_16x16x32_bf16 v[12:15], v[146:149], v[154:157], v[12:15]
	s_lshl_b32 s0, s0, 7
	s_waitcnt lgkmcnt(2)
	v_mfma_f32_16x16x32_bf16 v[32:35], v[146:149], v[174:177], v[32:35]
	s_waitcnt lgkmcnt(1)
	v_mfma_f32_16x16x32_bf16 v[52:55], v[146:149], v[178:181], v[52:55]
	s_waitcnt lgkmcnt(0)
	v_mfma_f32_16x16x32_bf16 v[56:59], v[146:149], v[182:185], v[56:59]
	v_mfma_f32_16x16x32_bf16 v[36:39], v[170:173], v[154:157], v[36:39]
	v_mfma_f32_16x16x32_bf16 v[40:43], v[170:173], v[174:177], v[40:43]
	v_mfma_f32_16x16x32_bf16 v[44:47], v[170:173], v[178:181], v[44:47]
	v_mfma_f32_16x16x32_bf16 v[48:51], v[170:173], v[182:185], v[48:51]
	ds_read_b128 v[146:149], v218 offset:4096
	ds_read_b128 v[170:173], v218 offset:6144
	s_waitcnt vmcnt(14)
	ds_write_b128 v215, v[64:67] offset:18432
	s_waitcnt vmcnt(14)
	ds_write_b128 v215, v[68:71] offset:55296
	s_waitcnt vmcnt(13)
	ds_write_b128 v215, v[72:75] offset:22528
	s_waitcnt vmcnt(10)
	ds_write_b128 v215, v[84:87] offset:59392
	ds_write_b128 v215, v[80:83] offset:26624
	s_waitcnt vmcnt(9)
	ds_write_b128 v215, v[88:91] offset:63488
	ds_write_b128 v215, v[76:79] offset:30720
	s_waitcnt vmcnt(8)
	ds_write_b128 v216, v[92:95] offset:12288
	s_waitcnt lgkmcnt(0)
	s_barrier
	ds_read_b128 v[64:67], v122 offset:18432
	v_mfma_f32_16x16x32_bf16 v[24:27], v[146:149], v[154:157], v[24:27]
	ds_read_b128 v[72:75], v109 offset:55296
	ds_read_b128 v[76:79], v109 offset:57344
	ds_read_b128 v[92:95], v109 offset:59392
	v_mfma_f32_16x16x32_bf16 v[20:23], v[146:149], v[174:177], v[20:23]
	v_lshl_add_u64 v[68:69], v[102:103], 0, s[0:1]
	v_mfma_f32_16x16x32_bf16 v[16:19], v[146:149], v[178:181], v[16:19]
	v_mfma_f32_16x16x32_bf16 v[28:31], v[146:149], v[182:185], v[28:31]
	ds_read_b128 v[146:149], v109 offset:61440
	s_waitcnt lgkmcnt(3)
	v_mfma_f32_16x16x32_bf16 v[12:15], v[64:67], v[72:75], v[12:15]
	s_waitcnt lgkmcnt(2)
	v_mfma_f32_16x16x32_bf16 v[32:35], v[64:67], v[76:79], v[32:35]
	s_waitcnt lgkmcnt(1)
	v_mfma_f32_16x16x32_bf16 v[52:55], v[64:67], v[92:95], v[52:55]
	s_waitcnt lgkmcnt(0)
	v_mfma_f32_16x16x32_bf16 v[56:59], v[64:67], v[146:149], v[56:59]
	ds_read_b128 v[64:67], v122 offset:20480
	v_mfma_f32_16x16x32_bf16 v[0:3], v[170:173], v[154:157], v[0:3]
	ds_read_b128 v[80:83], v122 offset:22528
	ds_read_b128 v[154:157], v122 offset:24576
	global_load_dwordx4 v[68:71], v[68:69], off offset:384
	v_mfma_f32_16x16x32_bf16 v[4:7], v[170:173], v[174:177], v[4:7]
	v_mfma_f32_16x16x32_bf16 v[8:11], v[170:173], v[178:181], v[8:11]
	s_waitcnt lgkmcnt(2)
	v_mfma_f32_16x16x32_bf16 v[36:39], v[64:67], v[72:75], v[36:39]
	v_mfma_f32_16x16x32_bf16 v[40:43], v[64:67], v[76:79], v[40:43]
	v_mfma_f32_16x16x32_bf16 v[44:47], v[64:67], v[92:95], v[44:47]
	v_mfma_f32_16x16x32_bf16 v[48:51], v[64:67], v[146:149], v[48:51]
	v_lshl_add_u64 v[64:65], v[100:101], 0, s[0:1]
	s_addk_i32 s0, 0x180
	v_lshl_add_u64 v[84:85], v[106:107], 0, s[0:1]
	s_waitcnt lgkmcnt(1)
	v_mfma_f32_16x16x32_bf16 v[24:27], v[80:83], v[72:75], v[24:27]
	v_lshl_add_u64 v[86:87], v[124:125], 0, s[0:1]
	v_lshl_add_u64 v[88:89], v[126:127], 0, s[0:1]
	global_load_dwordx4 v[64:67], v[64:65], off offset:384
	v_mfma_f32_16x16x32_bf16 v[20:23], v[80:83], v[76:79], v[20:23]
	v_mfma_f32_16x16x32_bf16 v[16:19], v[80:83], v[92:95], v[16:19]
	v_mfma_f32_16x16x32_bf16 v[28:31], v[80:83], v[146:149], v[28:31]
	v_lshl_add_u64 v[80:81], v[118:119], 0, s[0:1]
	v_mfma_f32_16x16x32_bf16 v[60:63], v[170:173], v[182:185], v[60:63]
	v_lshl_add_u64 v[170:171], v[120:121], 0, s[0:1]
	v_lshl_add_u64 v[172:173], v[128:129], 0, s[0:1]
	s_waitcnt lgkmcnt(0)
	v_mfma_f32_16x16x32_bf16 v[0:3], v[154:157], v[72:75], v[0:3]
	global_load_dwordx4 v[72:75], v[84:85], off
	s_nop 0
	global_load_dwordx4 v[84:87], v[86:87], off
	v_mfma_f32_16x16x32_bf16 v[4:7], v[154:157], v[76:79], v[4:7]
	global_load_dwordx4 v[80:83], v[80:81], off
	s_nop 0
	global_load_dwordx4 v[88:91], v[88:89], off
	s_nop 0
	global_load_dwordx4 v[76:79], v[170:171], off
	v_mfma_f32_16x16x32_bf16 v[8:11], v[154:157], v[92:95], v[8:11]
	global_load_dwordx4 v[92:95], v[172:173], off
	v_mfma_f32_16x16x32_bf16 v[60:63], v[154:157], v[146:149], v[60:63]
	ds_read_b128 v[146:149], v218 offset:18432
	ds_read_b128 v[154:157], v219 offset:55296
	ds_read_b128 v[170:173], v218 offset:20480
	ds_read_b128 v[174:177], v219 offset:57344
	ds_read_b128 v[178:181], v219 offset:59392
	ds_read_b128 v[182:185], v219 offset:61440
	s_addk_i32 s11, 0x80
	s_waitcnt lgkmcnt(4)
	v_mfma_f32_16x16x32_bf16 v[12:15], v[146:149], v[154:157], v[12:15]
	s_mov_b32 s13, s21
	s_waitcnt lgkmcnt(2)
	v_mfma_f32_16x16x32_bf16 v[32:35], v[146:149], v[174:177], v[32:35]
	s_waitcnt lgkmcnt(1)
	v_mfma_f32_16x16x32_bf16 v[52:55], v[146:149], v[178:181], v[52:55]
	s_waitcnt lgkmcnt(0)
	v_mfma_f32_16x16x32_bf16 v[56:59], v[146:149], v[182:185], v[56:59]
	v_mfma_f32_16x16x32_bf16 v[36:39], v[170:173], v[154:157], v[36:39]
	v_mfma_f32_16x16x32_bf16 v[40:43], v[170:173], v[174:177], v[40:43]
	v_mfma_f32_16x16x32_bf16 v[44:47], v[170:173], v[178:181], v[44:47]
	v_mfma_f32_16x16x32_bf16 v[48:51], v[170:173], v[182:185], v[48:51]
	ds_read_b128 v[146:149], v218 offset:22528
	ds_read_b128 v[170:173], v218 offset:24576
	s_waitcnt vmcnt(13)
	ds_write_b128 v215, v[130:133]
	ds_write_b128 v215, v[158:161] offset:36864
	ds_write_b128 v215, v[162:165] offset:4096
	s_waitcnt vmcnt(12)
	ds_write_b128 v215, v[150:153] offset:40960
	s_waitcnt lgkmcnt(5)
	v_mfma_f32_16x16x32_bf16 v[24:27], v[146:149], v[154:157], v[24:27]
	s_waitcnt vmcnt(11)
	ds_write_b128 v215, v[134:137] offset:8192
	s_waitcnt vmcnt(10)
	ds_write_b128 v215, v[166:169] offset:45056
	s_waitcnt vmcnt(9)
	ds_write_b128 v215, v[138:141] offset:12288
	s_waitcnt vmcnt(8)
	ds_write_b128 v215, v[142:145] offset:49152
	s_waitcnt lgkmcnt(0)
	v_mfma_f32_16x16x32_bf16 v[20:23], v[146:149], v[174:177], v[20:23]
	s_barrier
	v_mfma_f32_16x16x32_bf16 v[16:19], v[146:149], v[178:181], v[16:19]
	v_mfma_f32_16x16x32_bf16 v[28:31], v[146:149], v[182:185], v[28:31]
	v_mfma_f32_16x16x32_bf16 v[0:3], v[170:173], v[154:157], v[0:3]
	v_mfma_f32_16x16x32_bf16 v[4:7], v[170:173], v[174:177], v[4:7]
	v_mfma_f32_16x16x32_bf16 v[8:11], v[170:173], v[178:181], v[8:11]
	v_mfma_f32_16x16x32_bf16 v[60:63], v[170:173], v[182:185], v[60:63]
	s_cbranch_vccnz .LBB0_913
	s_lshl_b32 s0, s8, 2
	s_add_u32 s8, s36, s0
	s_waitcnt vmcnt(6)
	v_or_b32_e32 v64, s9, v112
	s_addc_u32 s9, s37, 0
	s_lshl_b32 s10, s10, 2
	s_add_u32 s8, s8, s10
	v_add_u32_e32 v116, s12, v64
	s_addc_u32 s9, s9, 0
	v_mov_b32_e32 v115, v117
	v_lshl_add_u64 v[64:65], s[8:9], 0, v[114:115]
	v_lshlrev_b64 v[66:67], 12, v[116:117]
	v_lshl_add_u64 v[68:69], v[64:65], 0, v[66:67]
	v_or_b32_e32 v70, 0x1000, v66
	v_mov_b32_e32 v71, v67
	s_waitcnt vmcnt(5)
	v_lshl_add_u64 v[72:73], v[64:65], 0, v[70:71]
	global_load_dword v106, v[68:69], off
	global_load_dword v107, v[68:69], off offset:64
	global_load_dword v109, v[68:69], off offset:128
	global_load_dword v111, v[68:69], off offset:192
	global_load_dword v113, v[72:73], off
	global_load_dword v116, v[72:73], off offset:64
	global_load_dword v118, v[72:73], off offset:128
	global_load_dword v119, v[72:73], off offset:192
	v_or_b32_e32 v68, 0x2000, v66
	v_mov_b32_e32 v69, v67
	v_lshl_add_u64 v[72:73], v[64:65], 0, v[68:69]
	v_or_b32_e32 v74, 0x3000, v66
	v_mov_b32_e32 v75, v67
	s_waitcnt vmcnt(9)
	v_lshl_add_u64 v[76:77], v[64:65], 0, v[74:75]
	global_load_dword v120, v[72:73], off
	global_load_dword v121, v[72:73], off offset:64
	global_load_dword v122, v[72:73], off offset:128
	global_load_dword v123, v[72:73], off offset:192
	global_load_dword v124, v[76:77], off
	global_load_dword v125, v[76:77], off offset:64
	global_load_dword v126, v[76:77], off offset:128
	global_load_dword v127, v[76:77], off offset:192
	v_or_b32_e32 v72, 0x10000, v66
	v_mov_b32_e32 v73, v67
	v_lshl_add_u64 v[76:77], v[64:65], 0, v[72:73]
	v_or_b32_e32 v78, 0x11000, v66
	v_mov_b32_e32 v79, v67
	v_lshl_add_u64 v[80:81], v[64:65], 0, v[78:79]
	global_load_dword v128, v[76:77], off
	global_load_dword v129, v[76:77], off offset:64
	global_load_dword v130, v[76:77], off offset:128
	global_load_dword v131, v[76:77], off offset:192
	global_load_dword v132, v[80:81], off
	global_load_dword v133, v[80:81], off offset:64
	global_load_dword v134, v[80:81], off offset:128
	global_load_dword v135, v[80:81], off offset:192
	v_or_b32_e32 v76, 0x12000, v66
	v_mov_b32_e32 v77, v67
	v_lshl_add_u64 v[80:81], v[64:65], 0, v[76:77]
	v_or_b32_e32 v82, 0x13000, v66
	v_mov_b32_e32 v83, v67
	v_lshl_add_u64 v[84:85], v[64:65], 0, v[82:83]
	global_load_dword v136, v[80:81], off
	global_load_dword v137, v[80:81], off offset:64
	global_load_dword v138, v[80:81], off offset:128
	global_load_dword v139, v[80:81], off offset:192
	global_load_dword v140, v[84:85], off
	global_load_dword v141, v[84:85], off offset:64
	global_load_dword v142, v[84:85], off offset:128
	global_load_dword v143, v[84:85], off offset:192
	v_or_b32_e32 v80, 0x20000, v66
	v_mov_b32_e32 v81, v67
	v_lshl_add_u64 v[84:85], v[64:65], 0, v[80:81]
	v_or_b32_e32 v86, 0x21000, v66
	v_mov_b32_e32 v87, v67
	v_lshl_add_u64 v[88:89], v[64:65], 0, v[86:87]
	global_load_dword v144, v[84:85], off
	global_load_dword v145, v[84:85], off offset:64
	global_load_dword v146, v[84:85], off offset:128
	global_load_dword v147, v[84:85], off offset:192
	global_load_dword v148, v[88:89], off
	global_load_dword v149, v[88:89], off offset:64
	global_load_dword v150, v[88:89], off offset:128
	global_load_dword v151, v[88:89], off offset:192
	v_or_b32_e32 v84, 0x22000, v66
	v_mov_b32_e32 v85, v67
	v_lshl_add_u64 v[88:89], v[64:65], 0, v[84:85]
	v_or_b32_e32 v90, 0x23000, v66
	v_mov_b32_e32 v91, v67
	s_waitcnt vmcnt(40)
	v_lshl_add_u64 v[92:93], v[64:65], 0, v[90:91]
	global_load_dword v152, v[88:89], off
	global_load_dword v153, v[88:89], off offset:64
	global_load_dword v154, v[88:89], off offset:128
	global_load_dword v155, v[88:89], off offset:192
	global_load_dword v156, v[92:93], off
	global_load_dword v157, v[92:93], off offset:64
	global_load_dword v158, v[92:93], off offset:128
	global_load_dword v159, v[92:93], off offset:192
	v_or_b32_e32 v88, 0x30000, v66
	v_mov_b32_e32 v89, v67
	v_lshl_add_u64 v[92:93], v[64:65], 0, v[88:89]
	v_or_b32_e32 v94, 0x31000, v66
	v_mov_b32_e32 v95, v67
	v_lshl_add_u64 v[100:101], v[64:65], 0, v[94:95]
	global_load_dword v160, v[92:93], off
	global_load_dword v161, v[92:93], off offset:64
	global_load_dword v162, v[92:93], off offset:128
	global_load_dword v163, v[92:93], off offset:192
	global_load_dword v164, v[100:101], off
	global_load_dword v165, v[100:101], off offset:64
	global_load_dword v166, v[100:101], off offset:128
	global_load_dword v167, v[100:101], off offset:192
	v_or_b32_e32 v92, 0x32000, v66
	v_mov_b32_e32 v93, v67
	v_lshl_add_u64 v[100:101], v[64:65], 0, v[92:93]
	v_or_b32_e32 v102, 0x33000, v66
	v_mov_b32_e32 v103, v67
	v_lshl_add_u64 v[64:65], v[64:65], 0, v[102:103]
	global_load_dword v168, v[100:101], off
	global_load_dword v169, v[100:101], off offset:64
	global_load_dword v170, v[100:101], off offset:128
	s_nop 0
	global_load_dword v100, v[100:101], off offset:192
	s_nop 0
	global_load_dword v101, v[64:65], off
	global_load_dword v171, v[64:65], off offset:64
	global_load_dword v172, v[64:65], off offset:128
	global_load_dword v173, v[64:65], off offset:192
	s_add_u32 s0, s52, s0
	s_addc_u32 s9, s53, 0
	s_add_u32 s8, s0, s10
	s_addc_u32 s9, s9, 0
	v_lshl_add_u64 v[64:65], s[8:9], 0, v[114:115]
	v_lshl_add_u64 v[66:67], v[64:65], 0, v[66:67]
	s_waitcnt vmcnt(62)
	v_add_f32_e32 v12, v12, v106
	global_store_dword v[66:67], v12, off
	v_add_f32_e32 v12, v32, v107
	global_store_dword v[66:67], v12, off offset:64
	s_waitcnt vmcnt(62)
	v_add_f32_e32 v12, v52, v109
	global_store_dword v[66:67], v12, off offset:128
	v_add_f32_e32 v12, v56, v111
	global_store_dword v[66:67], v12, off offset:192
	v_lshl_add_u64 v[66:67], v[64:65], 0, v[70:71]
	s_waitcnt vmcnt(62)
	v_add_f32_e32 v12, v13, v113
	global_store_dword v[66:67], v12, off
	v_add_f32_e32 v12, v33, v116
	global_store_dword v[66:67], v12, off offset:64
	s_waitcnt vmcnt(62)
	v_add_f32_e32 v12, v53, v118
	global_store_dword v[66:67], v12, off offset:128
	v_add_f32_e32 v12, v57, v119
	global_store_dword v[66:67], v12, off offset:192
	v_lshl_add_u64 v[12:13], v[64:65], 0, v[68:69]
	s_waitcnt vmcnt(62)
	v_add_f32_e32 v14, v14, v120
	global_store_dword v[12:13], v14, off
	v_add_f32_e32 v14, v34, v121
	global_store_dword v[12:13], v14, off offset:64
	s_waitcnt vmcnt(62)
	v_add_f32_e32 v14, v54, v122
	global_store_dword v[12:13], v14, off offset:128
	v_add_f32_e32 v14, v58, v123
	global_store_dword v[12:13], v14, off offset:192
	v_lshl_add_u64 v[12:13], v[64:65], 0, v[74:75]
	s_waitcnt vmcnt(62)
	v_add_f32_e32 v14, v15, v124
	global_store_dword v[12:13], v14, off
	v_add_f32_e32 v14, v35, v125
	global_store_dword v[12:13], v14, off offset:64
	s_waitcnt vmcnt(62)
	v_add_f32_e32 v14, v55, v126
	global_store_dword v[12:13], v14, off offset:128
	v_add_f32_e32 v14, v59, v127
	global_store_dword v[12:13], v14, off offset:192
	v_lshl_add_u64 v[12:13], v[64:65], 0, v[72:73]
	s_waitcnt vmcnt(62)
	v_add_f32_e32 v14, v36, v128
	global_store_dword v[12:13], v14, off
	v_add_f32_e32 v14, v40, v129
	global_store_dword v[12:13], v14, off offset:64
	s_waitcnt vmcnt(62)
	v_add_f32_e32 v14, v44, v130
	global_store_dword v[12:13], v14, off offset:128
	v_add_f32_e32 v14, v48, v131
	global_store_dword v[12:13], v14, off offset:192
	v_lshl_add_u64 v[12:13], v[64:65], 0, v[78:79]
	s_waitcnt vmcnt(62)
	v_add_f32_e32 v14, v37, v132
	global_store_dword v[12:13], v14, off
	v_add_f32_e32 v14, v41, v133
	global_store_dword v[12:13], v14, off offset:64
	s_waitcnt vmcnt(62)
	v_add_f32_e32 v14, v45, v134
	global_store_dword v[12:13], v14, off offset:128
	v_add_f32_e32 v14, v49, v135
	global_store_dword v[12:13], v14, off offset:192
	v_lshl_add_u64 v[12:13], v[64:65], 0, v[76:77]
	s_waitcnt vmcnt(62)
	v_add_f32_e32 v14, v38, v136
	global_store_dword v[12:13], v14, off
	v_add_f32_e32 v14, v42, v137
	global_store_dword v[12:13], v14, off offset:64
	s_waitcnt vmcnt(62)
	v_add_f32_e32 v14, v46, v138
	global_store_dword v[12:13], v14, off offset:128
	v_add_f32_e32 v14, v50, v139
	global_store_dword v[12:13], v14, off offset:192
	v_lshl_add_u64 v[12:13], v[64:65], 0, v[82:83]
	s_waitcnt vmcnt(62)
	v_add_f32_e32 v14, v39, v140
	global_store_dword v[12:13], v14, off
	v_add_f32_e32 v14, v43, v141
	global_store_dword v[12:13], v14, off offset:64
	s_waitcnt vmcnt(62)
	v_add_f32_e32 v14, v47, v142
	global_store_dword v[12:13], v14, off offset:128
	v_add_f32_e32 v14, v51, v143
	global_store_dword v[12:13], v14, off offset:192
	v_lshl_add_u64 v[12:13], v[64:65], 0, v[80:81]
	s_waitcnt vmcnt(62)
	v_add_f32_e32 v14, v24, v144
	global_store_dword v[12:13], v14, off
	v_add_f32_e32 v14, v20, v145
	global_store_dword v[12:13], v14, off offset:64
	s_waitcnt vmcnt(62)
	v_add_f32_e32 v14, v16, v146
	global_store_dword v[12:13], v14, off offset:128
	v_add_f32_e32 v14, v28, v147
	global_store_dword v[12:13], v14, off offset:192
	v_lshl_add_u64 v[12:13], v[64:65], 0, v[86:87]
	s_waitcnt vmcnt(62)
	v_add_f32_e32 v14, v25, v148
	global_store_dword v[12:13], v14, off
	v_add_f32_e32 v14, v21, v149
	global_store_dword v[12:13], v14, off offset:64
	s_waitcnt vmcnt(62)
	v_add_f32_e32 v14, v17, v150
	global_store_dword v[12:13], v14, off offset:128
	v_add_f32_e32 v14, v29, v151
	global_store_dword v[12:13], v14, off offset:192
	v_lshl_add_u64 v[12:13], v[64:65], 0, v[84:85]
	s_waitcnt vmcnt(62)
	v_add_f32_e32 v14, v26, v152
	global_store_dword v[12:13], v14, off
	v_add_f32_e32 v14, v22, v153
	global_store_dword v[12:13], v14, off offset:64
	s_waitcnt vmcnt(62)
	v_add_f32_e32 v14, v18, v154
	global_store_dword v[12:13], v14, off offset:128
	v_add_f32_e32 v14, v30, v155
	global_store_dword v[12:13], v14, off offset:192
	v_lshl_add_u64 v[12:13], v[64:65], 0, v[90:91]
	s_waitcnt vmcnt(62)
	v_add_f32_e32 v14, v27, v156
	global_store_dword v[12:13], v14, off
	v_add_f32_e32 v14, v23, v157
	global_store_dword v[12:13], v14, off offset:64
	s_waitcnt vmcnt(62)
	v_add_f32_e32 v14, v19, v158
	global_store_dword v[12:13], v14, off offset:128
	v_add_f32_e32 v14, v31, v159
	global_store_dword v[12:13], v14, off offset:192
	v_lshl_add_u64 v[12:13], v[64:65], 0, v[88:89]
	s_waitcnt vmcnt(62)
	v_add_f32_e32 v0, v0, v160
	global_store_dword v[12:13], v0, off
	v_add_f32_e32 v0, v4, v161
	global_store_dword v[12:13], v0, off offset:64
	s_waitcnt vmcnt(62)
	v_add_f32_e32 v0, v8, v162
	global_store_dword v[12:13], v0, off offset:128
	v_add_f32_e32 v0, v60, v163
	global_store_dword v[12:13], v0, off offset:192
	v_lshl_add_u64 v[12:13], v[64:65], 0, v[94:95]
	s_waitcnt vmcnt(62)
	v_add_f32_e32 v0, v1, v164
	global_store_dword v[12:13], v0, off
	v_add_f32_e32 v0, v5, v165
	global_store_dword v[12:13], v0, off offset:64
	s_waitcnt vmcnt(62)
	v_add_f32_e32 v0, v9, v166
	global_store_dword v[12:13], v0, off offset:128
	v_add_f32_e32 v0, v61, v167
	global_store_dword v[12:13], v0, off offset:192
	v_lshl_add_u64 v[0:1], v[64:65], 0, v[92:93]
	s_waitcnt vmcnt(62)
	v_add_f32_e32 v2, v2, v168
	global_store_dword v[0:1], v2, off
	v_add_f32_e32 v2, v6, v169
	global_store_dword v[0:1], v2, off offset:64
	s_waitcnt vmcnt(62)
	v_add_f32_e32 v2, v10, v170
	global_store_dword v[0:1], v2, off offset:128
	v_add_f32_e32 v2, v62, v100
	global_store_dword v[0:1], v2, off offset:192
	v_lshl_add_u64 v[0:1], v[64:65], 0, v[102:103]
	s_waitcnt vmcnt(62)
	v_add_f32_e32 v2, v3, v101
	global_store_dword v[0:1], v2, off
	v_add_f32_e32 v2, v7, v171
	global_store_dword v[0:1], v2, off offset:64
	s_waitcnt vmcnt(62)
	v_add_f32_e32 v2, v11, v172
	global_store_dword v[0:1], v2, off offset:128
	v_add_f32_e32 v2, v63, v173
	global_store_dword v[0:1], v2, off offset:192
	s_branch .LBB0_892
